# K-loops: static s_setprio 1 for waves 4-7 (wr=1 half) through the K-loop, waves 0-3 at 0; no per-segment toggles
# speedup vs baseline: 1.0058x; 1.0006x over previous
; #define PG8_STAGE(bufoff, gbase, voff) do { _Pragma("unroll") for (int _i = 0; _i < 2; ++_i) \
;         __builtin_amdgcn_global_load_lds((const unsigned*)((const char*)(gbase) + (voff)[_i]), (LAS unsigned*)(lds + (bufoff) + ldsw + _i * 8192), 16, 0, 0); } while (0)
; #define PG8_LDA(dst, b, h) do { _Pragma("unroll") for (int m = 0; m < 4; ++m) _Pragma("unroll") for (int k = 0; k < 2; ++k) dst[m][k] = *(const LAS bf16x8*)(lds + PG8_SA(b, h) + aoff + m * 2048 + k * 1024); } while (0)
; #define PG8_LDB(dst, b, h) do { _Pragma("unroll") for (int n = 0; n < 2; ++n) _Pragma("unroll") for (int k = 0; k < 2; ++k) dst[n][k] = *(const LAS bf16x8*)(lds + PG8_SB(b, h) + boff + n * 2048 + k * 1024); } while (0)
; #define PG8_MMA(ai, bj, At, Bt) do { __builtin_amdgcn_s_setprio(1); _Pragma("unroll") for (int m = 0; m < 4; ++m) _Pragma("unroll") for (int n = 0; n < 2; ++n) _Pragma("unroll") for (int k = 0; k < 2; ++k) \
;         acc[ai][bj][m][n] = __builtin_amdgcn_mfma_f32_16x16x32_bf16(Bt[n][k], At[m][k], acc[ai][bj][m][n], 0, 0, 0); __builtin_amdgcn_s_setprio(0); } while (0)
; #define PG8_WAIT_V(n) asm volatile("s_waitcnt vmcnt(" #n ")" ::: "memory")
; #define PG8_WAIT_L(n) asm volatile("s_waitcnt lgkmcnt(" #n ")" ::: "memory")
; #define PG8_BAR __builtin_amdgcn_s_barrier()
; #define PG8_SCHED __builtin_amdgcn_sched_barrier(0)
; template <class Epi, class Sched, bool ALIGN_EPI>
; __device__ __forceinline__ void gemm_phase(LAS unsigned char* lds, const int wid, const int lda_, const int ldb_, const int K_, const Sched& S, const Epi& E) {
;     ...
;         const bool has_next = S.next(ui + 1, nxt);
;         const int nt = S.nt(cur);
;         const char* nA = has_next ? S.a(nxt) : cA; const char* nB = has_next ? S.b(nxt) : cB;
; #pragma unroll 1
;         for (int t = 0; t < nt; t += 2) {
;             const bool last = (t == nt - 2);
;             const char* a1 = cA + (size_t)(t + 1) * kstep;
;             const char* a2 = last ? nA : cA + (size_t)(t + 2) * kstep; const char* b2 = last ? nB : cB + (size_t)(t + 2) * kstep;
;             const char* a3 = a2 + kstep; const char* b3 = b2 + kstep;
;             PG8_LDB(B0, 0, 0); PG8_LDB(B1, 0, 1); PG8_SCHED; PG8_LDA(At, 0, 0); PG8_STAGE(PG8_SA(1, 1), a1 + hstepA, voffA);
;             PG8_WAIT_V(8); PG8_WAIT_L(0); PG8_BAR; PG8_MMA(0, 0, At, B0); PG8_MMA(0, 1, At, B1); PG8_BAR; PG8_SCHED;
.LBB0_298:
	s_ashr_i32 s37, s36, 31
	s_xor_b64 s[40:41], s[4:5], -1
	s_lshl_b64 s[38:39], s[36:37], 20
	v_readlane_b32 s42, v253, 52
	v_readlane_b32 s43, v253, 53
	s_add_u32 s38, s42, s38
	s_addc_u32 s39, s43, s39
	s_and_b64 s[42:43], s[4:5], exec
	s_cselect_b32 s31, s39, s47
	s_cselect_b32 s37, s38, s46
	s_ashr_i32 s35, s34, 31
	s_lshl_b64 s[42:43], s[34:35], 20
	s_add_u32 s42, s7, s42
	s_addc_u32 s43, s14, s43
	s_and_b64 s[4:5], s[4:5], exec
	s_cselect_b32 s4, s43, s49
	s_cselect_b32 s5, s42, s48
	s_add_u32 s50, s46, 0x80
	s_addc_u32 s51, s47, 0
	s_add_u32 s35, s48, 0x100
	v_lshl_add_u64 v[156:157], s[50:51], 0, v[152:153]
	v_lshl_add_u64 v[158:159], s[50:51], 0, v[154:155]
	s_addc_u32 s45, s49, 0
	s_mov_b32 s76, -2
	s_mov_b64 s[48:49], 0
	s_add_u32 s17, s46, s48
	s_addc_u32 s27, s47, s49
	s_add_u32 s17, s17, 0x100
	s_addc_u32 s27, s27, 0
	s_add_u32 s77, s35, s48
	s_addc_u32 s78, s45, s49
	s_add_i32 s80, 0, 0x10000
	s_cmpk_eq_i32 s48, 0xf00
	s_cselect_b32 s51, s31, s27
	s_cselect_b32 s50, s37, s17
	v_add_u32_e32 v141, s80, v135
	s_cselect_b32 s79, s4, s78
	s_cselect_b32 s78, s5, s77
	s_add_i32 s17, 0, 0x14000
	ds_read_b128 v[160:163], v141
	ds_read_b128 v[164:167], v141 offset:1024
	ds_read_b128 v[168:171], v141 offset:2048
	ds_read_b128 v[172:175], v141 offset:3072
	v_add_u32_e32 v141, s17, v135
	ds_read_b128 v[180:183], v141
	ds_read_b128 v[184:187], v141 offset:1024
	ds_read_b128 v[188:191], v141 offset:2048
	ds_read_b128 v[192:195], v141 offset:3072
	v_lshl_add_u64 v[228:229], v[158:159], 0, s[48:49]
	s_add_i32 m0, s16, 0xc000
	ds_read_b128 v[196:199], v139
	ds_read_b128 v[200:203], v139 offset:1024
	ds_read_b128 v[204:207], v139 offset:2048
	ds_read_b128 v[208:211], v139 offset:3072
	ds_read_b128 v[212:215], v139 offset:4096
	ds_read_b128 v[216:219], v139 offset:5120
	ds_read_b128 v[220:223], v139 offset:6144
	ds_read_b128 v[224:227], v139 offset:7168
	global_load_lds_dwordx4 v[228:229], off
	v_lshl_add_u64 v[228:229], v[156:157], 0, s[48:49]
	s_add_i32 m0, s16, 0xe000
	s_nop 0
	global_load_lds_dwordx4 v[228:229], off
	s_waitcnt vmcnt(8)
	s_waitcnt lgkmcnt(0)
	s_barrier
	v_readlane_b32 s101, v252, 58
	s_setprio 0
	s_cmp_eq_u32 s101, 0
	s_cbranch_scc1 .Lprio_dn_299
	s_setprio 1
; #define PG8_STAGE(bufoff, gbase, voff) do { _Pragma("unroll") for (int _i = 0; _i < 2; ++_i) \
;         __builtin_amdgcn_global_load_lds((const unsigned*)((const char*)(gbase) + (voff)[_i]), (LAS unsigned*)(lds + (bufoff) + ldsw + _i * 8192), 16, 0, 0); } while (0)
; #define PG8_LDA(dst, b, h) do { _Pragma("unroll") for (int m = 0; m < 4; ++m) _Pragma("unroll") for (int k = 0; k < 2; ++k) dst[m][k] = *(const LAS bf16x8*)(lds + PG8_SA(b, h) + aoff + m * 2048 + k * 1024); } while (0)
; #define PG8_MMA(ai, bj, At, Bt) do { __builtin_amdgcn_s_setprio(1); _Pragma("unroll") for (int m = 0; m < 4; ++m) _Pragma("unroll") for (int n = 0; n < 2; ++n) _Pragma("unroll") for (int k = 0; k < 2; ++k) \
;         acc[ai][bj][m][n] = __builtin_amdgcn_mfma_f32_16x16x32_bf16(Bt[n][k], At[m][k], acc[ai][bj][m][n], 0, 0, 0); __builtin_amdgcn_s_setprio(0); } while (0)
; #define PG8_WAIT_V(n) asm volatile("s_waitcnt vmcnt(" #n ")" ::: "memory")
; #define PG8_WAIT_L(n) asm volatile("s_waitcnt lgkmcnt(" #n ")" ::: "memory")
; #define PG8_BAR __builtin_amdgcn_s_barrier()
; #define PG8_SCHED __builtin_amdgcn_sched_barrier(0)
; template <class Epi, class Sched, bool ALIGN_EPI>
; __device__ __forceinline__ void gemm_phase(LAS unsigned char* lds, const int wid, const int lda_, const int ldb_, const int K_, const Sched& S, const Epi& E) {
;     ...
;             PG8_WAIT_V(8); PG8_WAIT_L(0); PG8_BAR; PG8_MMA(0, 0, At, B0); PG8_MMA(0, 1, At, B1); PG8_BAR; PG8_SCHED;
;             PG8_LDA(At, 0, 1); PG8_STAGE(PG8_SB(0, 0), b2, voffB); PG8_STAGE(PG8_SB(0, 1), b2 + hstepB, voffB); PG8_STAGE(PG8_SA(0, 0), a2, voffA);
;             PG8_WAIT_V(8); PG8_WAIT_L(0); PG8_BAR; PG8_MMA(1, 0, At, B0); PG8_MMA(1, 1, At, B1); PG8_BAR; PG8_SCHED;
.Lprio_dn_299:
	s_waitcnt lgkmcnt(0)
	v_mfma_f32_16x16x32_bf16 v[124:127], v[160:163], v[196:199], 0
	v_mfma_f32_16x16x32_bf16 v[120:123], v[168:171], v[196:199], 0
	v_mfma_f32_16x16x32_bf16 v[116:119], v[160:163], v[204:207], 0
	v_mfma_f32_16x16x32_bf16 v[112:115], v[168:171], v[204:207], 0
	v_mfma_f32_16x16x32_bf16 v[100:103], v[160:163], v[212:215], 0
	v_mfma_f32_16x16x32_bf16 v[96:99], v[168:171], v[212:215], 0
	v_mfma_f32_16x16x32_bf16 v[84:87], v[160:163], v[220:223], 0
	v_mfma_f32_16x16x32_bf16 v[80:83], v[168:171], v[220:223], 0
	v_mfma_f32_16x16x32_bf16 v[124:127], v[164:167], v[200:203], v[124:127]
	v_mfma_f32_16x16x32_bf16 v[120:123], v[172:175], v[200:203], v[120:123]
	v_mfma_f32_16x16x32_bf16 v[116:119], v[164:167], v[208:211], v[116:119]
	v_mfma_f32_16x16x32_bf16 v[112:115], v[172:175], v[208:211], v[112:115]
	v_mfma_f32_16x16x32_bf16 v[100:103], v[164:167], v[216:219], v[100:103]
	v_mfma_f32_16x16x32_bf16 v[96:99], v[172:175], v[216:219], v[96:99]
	v_mfma_f32_16x16x32_bf16 v[84:87], v[164:167], v[224:227], v[84:87]
	v_mfma_f32_16x16x32_bf16 v[80:83], v[172:175], v[224:227], v[80:83]
	v_mfma_f32_16x16x32_bf16 v[108:111], v[180:183], v[196:199], 0
	v_mfma_f32_16x16x32_bf16 v[104:107], v[188:191], v[196:199], 0
	v_mfma_f32_16x16x32_bf16 v[92:95], v[180:183], v[204:207], 0
	v_mfma_f32_16x16x32_bf16 v[88:91], v[188:191], v[204:207], 0
	v_mfma_f32_16x16x32_bf16 v[76:79], v[180:183], v[212:215], 0
	v_mfma_f32_16x16x32_bf16 v[72:75], v[188:191], v[212:215], 0
	v_mfma_f32_16x16x32_bf16 v[68:71], v[180:183], v[220:223], 0
	v_mfma_f32_16x16x32_bf16 v[64:67], v[188:191], v[220:223], 0
	v_mfma_f32_16x16x32_bf16 v[108:111], v[184:187], v[200:203], v[108:111]
	v_mfma_f32_16x16x32_bf16 v[104:107], v[192:195], v[200:203], v[104:107]
	v_mfma_f32_16x16x32_bf16 v[92:95], v[184:187], v[208:211], v[92:95]
	v_mfma_f32_16x16x32_bf16 v[88:91], v[192:195], v[208:211], v[88:91]
	v_mfma_f32_16x16x32_bf16 v[76:79], v[184:187], v[216:219], v[76:79]
	v_mfma_f32_16x16x32_bf16 v[72:75], v[192:195], v[216:219], v[72:75]
	v_mfma_f32_16x16x32_bf16 v[68:71], v[184:187], v[224:227], v[68:71]
	v_mfma_f32_16x16x32_bf16 v[64:67], v[192:195], v[224:227], v[64:67]
	s_barrier
	s_add_i32 s27, s80, s3
	v_lshl_add_u64 v[228:229], s[78:79], 0, v[176:177]
	s_mov_b32 m0, s27
	ds_read_b128 v[196:199], v139 offset:16384
	ds_read_b128 v[200:203], v139 offset:17408
	ds_read_b128 v[204:207], v139 offset:18432
	ds_read_b128 v[208:211], v139 offset:19456
	ds_read_b128 v[212:215], v139 offset:20480
	ds_read_b128 v[216:219], v139 offset:21504
	ds_read_b128 v[220:223], v139 offset:22528
	ds_read_b128 v[224:227], v139 offset:23552
	global_load_lds_dwordx4 v[228:229], off
	s_add_i32 m0, s27, 0x2000
	v_lshl_add_u64 v[230:231], s[78:79], 0, v[128:129]
	s_add_u32 s78, s78, s10
	s_addc_u32 s79, s79, s11
	s_add_i32 s17, s17, s3
	global_load_lds_dwordx4 v[230:231], off
	v_lshl_add_u64 v[232:233], s[78:79], 0, v[176:177]
	s_mov_b32 m0, s17
	v_lshl_add_u64 v[234:235], s[78:79], 0, v[128:129]
	global_load_lds_dwordx4 v[232:233], off
	s_add_i32 m0, s17, 0x2000
	v_lshl_add_u64 v[236:237], s[50:51], 0, v[132:133]
	global_load_lds_dwordx4 v[234:235], off
	s_mov_b32 m0, s16
	v_lshl_add_u64 v[246:247], s[50:51], 0, v[130:131]
	global_load_lds_dwordx4 v[236:237], off
	s_mov_b32 m0, s15
	s_nop 0
	global_load_lds_dwordx4 v[246:247], off
	s_waitcnt vmcnt(8)
	s_waitcnt lgkmcnt(0)
	s_barrier
	s_waitcnt lgkmcnt(0)
	v_mfma_f32_16x16x32_bf16 v[60:63], v[160:163], v[196:199], 0
	v_mfma_f32_16x16x32_bf16 v[56:59], v[168:171], v[196:199], 0
	v_mfma_f32_16x16x32_bf16 v[52:55], v[160:163], v[204:207], 0
	v_mfma_f32_16x16x32_bf16 v[48:51], v[168:171], v[204:207], 0
	v_mfma_f32_16x16x32_bf16 v[36:39], v[160:163], v[212:215], 0
	v_mfma_f32_16x16x32_bf16 v[32:35], v[168:171], v[212:215], 0
	v_mfma_f32_16x16x32_bf16 v[20:23], v[160:163], v[220:223], 0
	v_mfma_f32_16x16x32_bf16 v[16:19], v[168:171], v[220:223], 0
	v_mfma_f32_16x16x32_bf16 v[60:63], v[164:167], v[200:203], v[60:63]
	v_mfma_f32_16x16x32_bf16 v[56:59], v[172:175], v[200:203], v[56:59]
	v_mfma_f32_16x16x32_bf16 v[52:55], v[164:167], v[208:211], v[52:55]
	v_mfma_f32_16x16x32_bf16 v[48:51], v[172:175], v[208:211], v[48:51]
	v_mfma_f32_16x16x32_bf16 v[36:39], v[164:167], v[216:219], v[36:39]
	v_mfma_f32_16x16x32_bf16 v[32:35], v[172:175], v[216:219], v[32:35]
	v_mfma_f32_16x16x32_bf16 v[20:23], v[164:167], v[224:227], v[20:23]
	v_mfma_f32_16x16x32_bf16 v[16:19], v[172:175], v[224:227], v[16:19]
	v_mfma_f32_16x16x32_bf16 v[44:47], v[180:183], v[196:199], 0
	v_mfma_f32_16x16x32_bf16 v[40:43], v[188:191], v[196:199], 0
	v_mfma_f32_16x16x32_bf16 v[28:31], v[180:183], v[204:207], 0
	v_mfma_f32_16x16x32_bf16 v[24:27], v[188:191], v[204:207], 0
	v_mfma_f32_16x16x32_bf16 v[12:15], v[180:183], v[212:215], 0
	v_mfma_f32_16x16x32_bf16 v[8:11], v[188:191], v[212:215], 0
	v_mfma_f32_16x16x32_bf16 v[4:7], v[180:183], v[220:223], 0
	v_mfma_f32_16x16x32_bf16 v[0:3], v[188:191], v[220:223], 0
	v_mfma_f32_16x16x32_bf16 v[44:47], v[184:187], v[200:203], v[44:47]
	v_mfma_f32_16x16x32_bf16 v[40:43], v[192:195], v[200:203], v[40:43]
	v_mfma_f32_16x16x32_bf16 v[28:31], v[184:187], v[208:211], v[28:31]
	v_mfma_f32_16x16x32_bf16 v[24:27], v[192:195], v[208:211], v[24:27]
	v_mfma_f32_16x16x32_bf16 v[12:15], v[184:187], v[216:219], v[12:15]
	v_mfma_f32_16x16x32_bf16 v[8:11], v[192:195], v[216:219], v[8:11]
	v_mfma_f32_16x16x32_bf16 v[4:7], v[184:187], v[224:227], v[4:7]
	v_mfma_f32_16x16x32_bf16 v[0:3], v[192:195], v[224:227], v[0:3]
	s_barrier
	s_branch .Lgemm_join_299

; #define PG8_STAGE(bufoff, gbase, voff) do { _Pragma("unroll") for (int _i = 0; _i < 2; ++_i) \
;         __builtin_amdgcn_global_load_lds((const unsigned*)((const char*)(gbase) + (voff)[_i]), (LAS unsigned*)(lds + (bufoff) + ldsw + _i * 8192), 16, 0, 0); } while (0)
; #define PG8_LDA(dst, b, h) do { _Pragma("unroll") for (int m = 0; m < 4; ++m) _Pragma("unroll") for (int k = 0; k < 2; ++k) dst[m][k] = *(const LAS bf16x8*)(lds + PG8_SA(b, h) + aoff + m * 2048 + k * 1024); } while (0)
; #define PG8_LDB(dst, b, h) do { _Pragma("unroll") for (int n = 0; n < 2; ++n) _Pragma("unroll") for (int k = 0; k < 2; ++k) dst[n][k] = *(const LAS bf16x8*)(lds + PG8_SB(b, h) + boff + n * 2048 + k * 1024); } while (0)
; #define PG8_MMA(ai, bj, At, Bt) do { __builtin_amdgcn_s_setprio(1); _Pragma("unroll") for (int m = 0; m < 4; ++m) _Pragma("unroll") for (int n = 0; n < 2; ++n) _Pragma("unroll") for (int k = 0; k < 2; ++k) \
;         acc[ai][bj][m][n] = __builtin_amdgcn_mfma_f32_16x16x32_bf16(Bt[n][k], At[m][k], acc[ai][bj][m][n], 0, 0, 0); __builtin_amdgcn_s_setprio(0); } while (0)
; #define PG8_WAIT_V(n) asm volatile("s_waitcnt vmcnt(" #n ")" ::: "memory")
; #define PG8_WAIT_L(n) asm volatile("s_waitcnt lgkmcnt(" #n ")" ::: "memory")
; #define PG8_BAR __builtin_amdgcn_s_barrier()
; #define PG8_SCHED __builtin_amdgcn_sched_barrier(0)
; template <class Epi, class Sched, bool ALIGN_EPI>
; __device__ __forceinline__ void gemm_phase(LAS unsigned char* lds, const int wid, const int lda_, const int ldb_, const int K_, const Sched& S, const Epi& E) {
;     ...
;         const bool has_next = S.next(ui + 1, nxt);
;         const int nt = S.nt(cur);
;         const char* nA = has_next ? S.a(nxt) : cA; const char* nB = has_next ? S.b(nxt) : cB;
; #pragma unroll 1
;         for (int t = 0; t < nt; t += 2) {
;             const bool last = (t == nt - 2);
;             const char* a1 = cA + (size_t)(t + 1) * kstep;
;             const char* a2 = last ? nA : cA + (size_t)(t + 2) * kstep; const char* b2 = last ? nB : cB + (size_t)(t + 2) * kstep;
;             const char* a3 = a2 + kstep; const char* b3 = b2 + kstep;
;             PG8_LDB(B0, 0, 0); PG8_LDB(B1, 0, 1); PG8_SCHED; PG8_LDA(At, 0, 0); PG8_STAGE(PG8_SA(1, 1), a1 + hstepA, voffA);
;             PG8_WAIT_V(8); PG8_WAIT_L(0); PG8_BAR; PG8_MMA(0, 0, At, B0); PG8_MMA(0, 1, At, B1); PG8_BAR; PG8_SCHED;
.LBB0_670:
	s_xor_b64 s[44:45], s[4:5], -1
	s_cmp_gt_i32 s38, -1
	s_cselect_b64 s[50:51], -1, 0
	s_cmp_lt_i32 s38, 0
	s_cselect_b32 s35, 64, 16
	s_max_i32 s17, s75, 0
	s_ashr_i32 s43, s42, 31
	s_lshl_b32 s17, s17, 11
	s_lshl_b64 s[46:47], s[42:43], 21
	v_readlane_b32 s48, v252, 62
	v_readlane_b32 s49, v252, 63
	s_add_u32 s27, s48, s46
	s_addc_u32 s37, s49, s47
	s_add_u32 s46, s27, s17
	s_addc_u32 s47, s37, 0
	s_and_b64 s[48:49], s[4:5], exec
	s_cselect_b32 s37, s47, s95
	s_cselect_b32 s39, s46, s94
	s_ashr_i32 s41, s40, 31
	s_lshl_b64 s[48:49], s[40:41], 21
	s_add_u32 s27, s6, s48
	s_addc_u32 s41, s7, s49
	s_add_u32 s48, s27, s17
	s_addc_u32 s49, s41, 0
	s_and_b64 s[4:5], s[4:5], exec
	s_cselect_b32 s4, s49, s97
	s_cselect_b32 s5, s48, s96
	s_add_i32 s41, s35, -2
	s_add_u32 s94, s94, 0x80
	s_addc_u32 s95, s95, 0
	s_add_u32 s43, s96, 0x100
	s_mov_b32 s77, 0
	s_addc_u32 s76, s97, 0
	s_add_i32 s78, s77, 2
	s_add_u32 s17, s94, 0x80
	s_addc_u32 s27, s95, 0
	s_add_i32 s79, 0, 0x10000
	s_cmp_eq_u32 s41, s77
	s_cselect_b32 s97, s37, s27
	s_cselect_b32 s96, s39, s17
	v_add_u32_e32 v141, s79, v135
	s_cselect_b32 s81, s4, s76
	s_cselect_b32 s80, s5, s43
	s_add_i32 s17, 0, 0x14000
	ds_read_b128 v[156:159], v141
	ds_read_b128 v[160:163], v141 offset:1024
	ds_read_b128 v[164:167], v141 offset:2048
	ds_read_b128 v[168:171], v141 offset:3072
	v_add_u32_e32 v141, s17, v135
	ds_read_b128 v[172:175], v141
	ds_read_b128 v[180:183], v141 offset:1024
	ds_read_b128 v[184:187], v141 offset:2048
	ds_read_b128 v[188:191], v141 offset:3072
	v_lshl_add_u64 v[224:225], s[94:95], 0, v[152:153]
	s_add_i32 m0, s16, 0xc000
	ds_read_b128 v[192:195], v139
	ds_read_b128 v[196:199], v139 offset:1024
	ds_read_b128 v[200:203], v139 offset:2048
	ds_read_b128 v[204:207], v139 offset:3072
	ds_read_b128 v[208:211], v139 offset:4096
	ds_read_b128 v[212:215], v139 offset:5120
	ds_read_b128 v[216:219], v139 offset:6144
	ds_read_b128 v[220:223], v139 offset:7168
	global_load_lds_dwordx4 v[224:225], off
	v_lshl_add_u64 v[224:225], s[94:95], 0, v[154:155]
	s_add_i32 m0, s16, 0xe000
	s_nop 0
	global_load_lds_dwordx4 v[224:225], off
	s_waitcnt vmcnt(8)
	s_waitcnt lgkmcnt(0)
	s_barrier
	v_readlane_b32 s101, v252, 58
	s_setprio 0
	s_cmp_eq_u32 s101, 0
	s_cbranch_scc1 .Lprio_dn_671
	s_setprio 1
; #define PG8_STAGE(bufoff, gbase, voff) do { _Pragma("unroll") for (int _i = 0; _i < 2; ++_i) \
;         __builtin_amdgcn_global_load_lds((const unsigned*)((const char*)(gbase) + (voff)[_i]), (LAS unsigned*)(lds + (bufoff) + ldsw + _i * 8192), 16, 0, 0); } while (0)
; #define PG8_LDA(dst, b, h) do { _Pragma("unroll") for (int m = 0; m < 4; ++m) _Pragma("unroll") for (int k = 0; k < 2; ++k) dst[m][k] = *(const LAS bf16x8*)(lds + PG8_SA(b, h) + aoff + m * 2048 + k * 1024); } while (0)
; #define PG8_MMA(ai, bj, At, Bt) do { __builtin_amdgcn_s_setprio(1); _Pragma("unroll") for (int m = 0; m < 4; ++m) _Pragma("unroll") for (int n = 0; n < 2; ++n) _Pragma("unroll") for (int k = 0; k < 2; ++k) \
;         acc[ai][bj][m][n] = __builtin_amdgcn_mfma_f32_16x16x32_bf16(Bt[n][k], At[m][k], acc[ai][bj][m][n], 0, 0, 0); __builtin_amdgcn_s_setprio(0); } while (0)
; #define PG8_WAIT_V(n) asm volatile("s_waitcnt vmcnt(" #n ")" ::: "memory")
; #define PG8_WAIT_L(n) asm volatile("s_waitcnt lgkmcnt(" #n ")" ::: "memory")
; #define PG8_BAR __builtin_amdgcn_s_barrier()
; #define PG8_SCHED __builtin_amdgcn_sched_barrier(0)
; template <class Epi, class Sched, bool ALIGN_EPI>
; __device__ __forceinline__ void gemm_phase(LAS unsigned char* lds, const int wid, const int lda_, const int ldb_, const int K_, const Sched& S, const Epi& E) {
;     ...
;             PG8_WAIT_V(8); PG8_WAIT_L(0); PG8_BAR; PG8_MMA(0, 0, At, B0); PG8_MMA(0, 1, At, B1); PG8_BAR; PG8_SCHED;
;             PG8_LDA(At, 0, 1); PG8_STAGE(PG8_SB(0, 0), b2, voffB); PG8_STAGE(PG8_SB(0, 1), b2 + hstepB, voffB); PG8_STAGE(PG8_SA(0, 0), a2, voffA);
;             PG8_WAIT_V(8); PG8_WAIT_L(0); PG8_BAR; PG8_MMA(1, 0, At, B0); PG8_MMA(1, 1, At, B1); PG8_BAR; PG8_SCHED;
.Lprio_dn_671:
	s_waitcnt lgkmcnt(0)
	v_mfma_f32_16x16x32_bf16 v[124:127], v[156:159], v[192:195], 0
	v_mfma_f32_16x16x32_bf16 v[120:123], v[164:167], v[192:195], 0
	v_mfma_f32_16x16x32_bf16 v[116:119], v[156:159], v[200:203], 0
	v_mfma_f32_16x16x32_bf16 v[112:115], v[164:167], v[200:203], 0
	v_mfma_f32_16x16x32_bf16 v[100:103], v[156:159], v[208:211], 0
	v_mfma_f32_16x16x32_bf16 v[96:99], v[164:167], v[208:211], 0
	v_mfma_f32_16x16x32_bf16 v[84:87], v[156:159], v[216:219], 0
	v_mfma_f32_16x16x32_bf16 v[80:83], v[164:167], v[216:219], 0
	v_mfma_f32_16x16x32_bf16 v[124:127], v[160:163], v[196:199], v[124:127]
	v_mfma_f32_16x16x32_bf16 v[120:123], v[168:171], v[196:199], v[120:123]
	v_mfma_f32_16x16x32_bf16 v[116:119], v[160:163], v[204:207], v[116:119]
	v_mfma_f32_16x16x32_bf16 v[112:115], v[168:171], v[204:207], v[112:115]
	v_mfma_f32_16x16x32_bf16 v[100:103], v[160:163], v[212:215], v[100:103]
	v_mfma_f32_16x16x32_bf16 v[96:99], v[168:171], v[212:215], v[96:99]
	v_mfma_f32_16x16x32_bf16 v[84:87], v[160:163], v[220:223], v[84:87]
	v_mfma_f32_16x16x32_bf16 v[80:83], v[168:171], v[220:223], v[80:83]
	v_mfma_f32_16x16x32_bf16 v[108:111], v[172:175], v[192:195], 0
	v_mfma_f32_16x16x32_bf16 v[104:107], v[184:187], v[192:195], 0
	v_mfma_f32_16x16x32_bf16 v[92:95], v[172:175], v[200:203], 0
	v_mfma_f32_16x16x32_bf16 v[88:91], v[184:187], v[200:203], 0
	v_mfma_f32_16x16x32_bf16 v[76:79], v[172:175], v[208:211], 0
	v_mfma_f32_16x16x32_bf16 v[72:75], v[184:187], v[208:211], 0
	v_mfma_f32_16x16x32_bf16 v[68:71], v[172:175], v[216:219], 0
	v_mfma_f32_16x16x32_bf16 v[64:67], v[184:187], v[216:219], 0
	v_mfma_f32_16x16x32_bf16 v[108:111], v[180:183], v[196:199], v[108:111]
	v_mfma_f32_16x16x32_bf16 v[104:107], v[188:191], v[196:199], v[104:107]
	v_mfma_f32_16x16x32_bf16 v[92:95], v[180:183], v[204:207], v[92:95]
	v_mfma_f32_16x16x32_bf16 v[88:91], v[188:191], v[204:207], v[88:91]
	v_mfma_f32_16x16x32_bf16 v[76:79], v[180:183], v[212:215], v[76:79]
	v_mfma_f32_16x16x32_bf16 v[72:75], v[188:191], v[212:215], v[72:75]
	v_mfma_f32_16x16x32_bf16 v[68:71], v[180:183], v[220:223], v[68:71]
	v_mfma_f32_16x16x32_bf16 v[64:67], v[188:191], v[220:223], v[64:67]
	s_barrier
	s_add_i32 s27, s79, s3
	v_lshl_add_u64 v[224:225], s[80:81], 0, v[176:177]
	s_mov_b32 m0, s27
	ds_read_b128 v[192:195], v139 offset:16384
	ds_read_b128 v[196:199], v139 offset:17408
	ds_read_b128 v[200:203], v139 offset:18432
	ds_read_b128 v[204:207], v139 offset:19456
	ds_read_b128 v[208:211], v139 offset:20480
	ds_read_b128 v[212:215], v139 offset:21504
	ds_read_b128 v[216:219], v139 offset:22528
	ds_read_b128 v[220:223], v139 offset:23552
	global_load_lds_dwordx4 v[224:225], off
	s_add_i32 m0, s27, 0x2000
	v_lshl_add_u64 v[226:227], s[80:81], 0, v[132:133]
	s_add_u32 s80, s80, s30
	s_addc_u32 s81, s81, s31
	s_add_i32 s17, s17, s3
	global_load_lds_dwordx4 v[226:227], off
	v_lshl_add_u64 v[228:229], s[80:81], 0, v[176:177]
	s_mov_b32 m0, s17
	v_lshl_add_u64 v[230:231], s[80:81], 0, v[132:133]
	global_load_lds_dwordx4 v[228:229], off
	s_add_i32 m0, s17, 0x2000
	v_lshl_add_u64 v[232:233], s[96:97], 0, v[128:129]
	global_load_lds_dwordx4 v[230:231], off
	s_mov_b32 m0, s16
	v_lshl_add_u64 v[234:235], s[96:97], 0, v[130:131]
	global_load_lds_dwordx4 v[232:233], off
	s_mov_b32 m0, s14
	s_nop 0
	global_load_lds_dwordx4 v[234:235], off
	s_waitcnt vmcnt(8)
	s_waitcnt lgkmcnt(0)
	s_barrier
	s_waitcnt lgkmcnt(0)
	v_mfma_f32_16x16x32_bf16 v[60:63], v[156:159], v[192:195], 0
	v_mfma_f32_16x16x32_bf16 v[56:59], v[164:167], v[192:195], 0
	v_mfma_f32_16x16x32_bf16 v[52:55], v[156:159], v[200:203], 0
	v_mfma_f32_16x16x32_bf16 v[48:51], v[164:167], v[200:203], 0
	v_mfma_f32_16x16x32_bf16 v[36:39], v[156:159], v[208:211], 0
	v_mfma_f32_16x16x32_bf16 v[32:35], v[164:167], v[208:211], 0
	v_mfma_f32_16x16x32_bf16 v[20:23], v[156:159], v[216:219], 0
	v_mfma_f32_16x16x32_bf16 v[16:19], v[164:167], v[216:219], 0
	v_mfma_f32_16x16x32_bf16 v[60:63], v[160:163], v[196:199], v[60:63]
	v_mfma_f32_16x16x32_bf16 v[56:59], v[168:171], v[196:199], v[56:59]
	v_mfma_f32_16x16x32_bf16 v[52:55], v[160:163], v[204:207], v[52:55]
	v_mfma_f32_16x16x32_bf16 v[48:51], v[168:171], v[204:207], v[48:51]
	v_mfma_f32_16x16x32_bf16 v[36:39], v[160:163], v[212:215], v[36:39]
	v_mfma_f32_16x16x32_bf16 v[32:35], v[168:171], v[212:215], v[32:35]
	v_mfma_f32_16x16x32_bf16 v[20:23], v[160:163], v[220:223], v[20:23]
	v_mfma_f32_16x16x32_bf16 v[16:19], v[168:171], v[220:223], v[16:19]
	v_mfma_f32_16x16x32_bf16 v[44:47], v[172:175], v[192:195], 0
	v_mfma_f32_16x16x32_bf16 v[40:43], v[184:187], v[192:195], 0
	v_mfma_f32_16x16x32_bf16 v[28:31], v[172:175], v[200:203], 0
	v_mfma_f32_16x16x32_bf16 v[24:27], v[184:187], v[200:203], 0
	v_mfma_f32_16x16x32_bf16 v[12:15], v[172:175], v[208:211], 0
	v_mfma_f32_16x16x32_bf16 v[8:11], v[184:187], v[208:211], 0
	v_mfma_f32_16x16x32_bf16 v[4:7], v[172:175], v[216:219], 0
	v_mfma_f32_16x16x32_bf16 v[0:3], v[184:187], v[216:219], 0
	v_mfma_f32_16x16x32_bf16 v[44:47], v[180:183], v[196:199], v[44:47]
	v_mfma_f32_16x16x32_bf16 v[40:43], v[188:191], v[196:199], v[40:43]
	v_mfma_f32_16x16x32_bf16 v[28:31], v[180:183], v[204:207], v[28:31]
	v_mfma_f32_16x16x32_bf16 v[24:27], v[188:191], v[204:207], v[24:27]
	v_mfma_f32_16x16x32_bf16 v[12:15], v[180:183], v[212:215], v[12:15]
	v_mfma_f32_16x16x32_bf16 v[8:11], v[188:191], v[212:215], v[8:11]
	v_mfma_f32_16x16x32_bf16 v[4:7], v[180:183], v[220:223], v[4:7]
	v_mfma_f32_16x16x32_bf16 v[0:3], v[188:191], v[220:223], v[0:3]
	s_barrier
	s_branch .Lgemm_join_671

; #define PG8_STAGE(bufoff, gbase, voff) do { _Pragma("unroll") for (int _i = 0; _i < 2; ++_i) \
;         __builtin_amdgcn_global_load_lds((const unsigned*)((const char*)(gbase) + (voff)[_i]), (LAS unsigned*)(lds + (bufoff) + ldsw + _i * 8192), 16, 0, 0); } while (0)
; #define PG8_LDA(dst, b, h) do { _Pragma("unroll") for (int m = 0; m < 4; ++m) _Pragma("unroll") for (int k = 0; k < 2; ++k) dst[m][k] = *(const LAS bf16x8*)(lds + PG8_SA(b, h) + aoff + m * 2048 + k * 1024); } while (0)
; #define PG8_LDB(dst, b, h) do { _Pragma("unroll") for (int n = 0; n < 2; ++n) _Pragma("unroll") for (int k = 0; k < 2; ++k) dst[n][k] = *(const LAS bf16x8*)(lds + PG8_SB(b, h) + boff + n * 2048 + k * 1024); } while (0)
; #define PG8_WAIT_V(n) asm volatile("s_waitcnt vmcnt(" #n ")" ::: "memory")
; #define PG8_WAIT_L(n) asm volatile("s_waitcnt lgkmcnt(" #n ")" ::: "memory")
; #define PG8_BAR __builtin_amdgcn_s_barrier()
; #define PG8_SCHED __builtin_amdgcn_sched_barrier(0)
; template <class Epi, class Sched, bool ALIGN_EPI>
; __device__ __forceinline__ void gemm_phase(LAS unsigned char* lds, const int wid, const int lda_, const int ldb_, const int K_, const Sched& S, const Epi& E) {
;     ...
;         const bool has_next = S.next(ui + 1, nxt);
;         const int nt = S.nt(cur);
;         const char* nA = has_next ? S.a(nxt) : cA; const char* nB = has_next ? S.b(nxt) : cB;
; #pragma unroll 1
;         for (int t = 0; t < nt; t += 2) {
;             const bool last = (t == nt - 2);
;             const char* a1 = cA + (size_t)(t + 1) * kstep;
;             const char* a2 = last ? nA : cA + (size_t)(t + 2) * kstep; const char* b2 = last ? nB : cB + (size_t)(t + 2) * kstep;
;             const char* a3 = a2 + kstep; const char* b3 = b2 + kstep;
;             PG8_LDB(B0, 0, 0); PG8_LDB(B1, 0, 1); PG8_SCHED; PG8_LDA(At, 0, 0); PG8_STAGE(PG8_SA(1, 1), a1 + hstepA, voffA);
;             PG8_WAIT_V(8); PG8_WAIT_L(0); PG8_BAR; PG8_MMA(0, 0, At, B0); PG8_MMA(0, 1, At, B1); PG8_BAR; PG8_SCHED;
;     __device__ __forceinline__ const char* a(const pg8::Unit& u) const { return (const char*)ws + WS_W1 + (size_t)(u.pm & 1) * 256 * 256 * 2; }
;     __device__ __forceinline__ const char* b(const pg8::Unit& u) const { return (const char*)ws + WS_A + ((size_t)u.pn * 256 * D + (size_t)(u.pm >> 1) * 256) * 2; }
.LBB0_696:
	v_mov_b64_e32 v[0:1], 0x480
	v_cmp_lt_i64_e32 vcc, s[4:5], v[0:1]
	s_lshl_b32 s4, s73, 17
	s_and_b32 s4, s4, 0x20000
	v_readlane_b32 s5, v253, 31
	s_add_u32 s34, s5, s4
	v_readlane_b32 s4, v253, 32
	s_addc_u32 s35, s4, 0
	s_and_b64 s[4:5], vcc, exec
	s_cselect_b32 s4, s35, s45
	s_cselect_b32 s5, s34, s44
	s_ashr_i32 s36, s73, 1
	s_ashr_i32 s31, s30, 31
	s_ashr_i32 s37, s36, 31
	s_lshl_b64 s[36:37], s[36:37], 9
	s_lshl_b64 s[42:43], s[30:31], 20
	v_readlane_b32 s46, v253, 52
	v_readlane_b32 s47, v253, 53
	s_add_u32 s31, s46, s42
	s_addc_u32 s42, s47, s43
	s_add_u32 s36, s31, s36
	s_addc_u32 s37, s42, s37
	s_and_b64 s[42:43], vcc, exec
	s_cselect_b32 s31, s37, s41
	s_cselect_b32 s76, s36, s40
	s_mov_b64 s[50:51], 0
	s_mov_b64 s[46:47], -1
	s_mov_b64 s[48:49], 0
	s_add_u32 s77, s44, s50
	s_addc_u32 s78, s45, s51
	s_add_u32 s79, s77, 0x100
	s_addc_u32 s80, s78, 0
	s_and_b64 s[42:43], s[48:49], exec
	s_cselect_b32 s95, s4, s80
	s_cselect_b32 s94, s5, s79
	s_add_u32 s42, s40, s50
	s_addc_u32 s43, s41, s51
	s_add_u32 s50, s42, 0x100
	s_addc_u32 s51, s43, 0
	s_add_i32 s93, 0, 0x10000
	s_and_b64 s[42:43], s[48:49], exec
	s_cselect_b32 s51, s31, s51
	s_cselect_b32 s50, s76, s50
	s_add_i32 s42, 0, 0x14000
	v_add_u32_e32 v141, s93, v135
	s_add_u32 vcc_lo, s77, s0
	ds_read_b128 v[152:155], v141
	ds_read_b128 v[156:159], v141 offset:1024
	ds_read_b128 v[160:163], v141 offset:2048
	ds_read_b128 v[164:167], v141 offset:3072
	v_add_u32_e32 v141, s42, v135
	s_addc_u32 vcc_hi, s78, s1
	s_add_i32 s87, s93, s3
	ds_read_b128 v[168:171], v141
	ds_read_b128 v[172:175], v141 offset:1024
	ds_read_b128 v[180:183], v141 offset:2048
	ds_read_b128 v[184:187], v141 offset:3072
	s_add_i32 m0, s16, 0xc000
	s_add_i32 s27, s16, 0xe000
	s_add_i32 s80, s87, 0x2000
	s_add_u32 s96, s50, s10
	s_addc_u32 s97, s51, s11
	s_add_i32 s86, s42, s3
	s_add_i32 s81, s86, 0x2000
	s_add_i32 s79, 0, 0x18000
	s_add_i32 s78, 0, 0x1c000
	s_add_u32 s48, s94, s0
	s_addc_u32 s49, s95, s1
	s_add_i32 s77, s79, s3
	s_add_i32 s93, s78, s3
	s_add_i32 s43, s77, 0x2000
	s_add_i32 s42, s93, 0x2000
	v_lshl_add_u64 v[220:221], vcc, 0, v[132:133]
	v_lshl_add_u64 v[220:221], v[220:221], 0, s[24:25]
	ds_read_b128 v[188:191], v139
	ds_read_b128 v[192:195], v139 offset:1024
	ds_read_b128 v[196:199], v139 offset:2048
	ds_read_b128 v[200:203], v139 offset:3072
	ds_read_b128 v[204:207], v139 offset:4096
	ds_read_b128 v[208:211], v139 offset:5120
	ds_read_b128 v[212:215], v139 offset:6144
	ds_read_b128 v[216:219], v139 offset:7168
	global_load_lds_dwordx4 v[220:221], off
	v_lshl_add_u64 v[220:221], vcc, 0, v[130:131]
	v_lshl_add_u64 v[220:221], v[220:221], 0, s[24:25]
	s_mov_b32 m0, s27
	s_nop 0
	global_load_lds_dwordx4 v[220:221], off
	s_waitcnt vmcnt(8)
	s_waitcnt lgkmcnt(0)
	s_barrier
	v_readlane_b32 s101, v252, 58
	s_setprio 0
	s_cmp_eq_u32 s101, 0
	s_cbranch_scc1 .Lprio_dn_697
	s_setprio 1
; #define PG8_STAGE(bufoff, gbase, voff) do { _Pragma("unroll") for (int _i = 0; _i < 2; ++_i) \
;         __builtin_amdgcn_global_load_lds((const unsigned*)((const char*)(gbase) + (voff)[_i]), (LAS unsigned*)(lds + (bufoff) + ldsw + _i * 8192), 16, 0, 0); } while (0)
; #define PG8_LDA(dst, b, h) do { _Pragma("unroll") for (int m = 0; m < 4; ++m) _Pragma("unroll") for (int k = 0; k < 2; ++k) dst[m][k] = *(const LAS bf16x8*)(lds + PG8_SA(b, h) + aoff + m * 2048 + k * 1024); } while (0)
; #define PG8_MMA(ai, bj, At, Bt) do { __builtin_amdgcn_s_setprio(1); _Pragma("unroll") for (int m = 0; m < 4; ++m) _Pragma("unroll") for (int n = 0; n < 2; ++n) _Pragma("unroll") for (int k = 0; k < 2; ++k) \
;         acc[ai][bj][m][n] = __builtin_amdgcn_mfma_f32_16x16x32_bf16(Bt[n][k], At[m][k], acc[ai][bj][m][n], 0, 0, 0); __builtin_amdgcn_s_setprio(0); } while (0)
; #define PG8_WAIT_V(n) asm volatile("s_waitcnt vmcnt(" #n ")" ::: "memory")
; #define PG8_WAIT_L(n) asm volatile("s_waitcnt lgkmcnt(" #n ")" ::: "memory")
; #define PG8_BAR __builtin_amdgcn_s_barrier()
; #define PG8_SCHED __builtin_amdgcn_sched_barrier(0)
; template <class Epi, class Sched, bool ALIGN_EPI>
; __device__ __forceinline__ void gemm_phase(LAS unsigned char* lds, const int wid, const int lda_, const int ldb_, const int K_, const Sched& S, const Epi& E) {
;     ...
;             PG8_WAIT_V(8); PG8_WAIT_L(0); PG8_BAR; PG8_MMA(0, 0, At, B0); PG8_MMA(0, 1, At, B1); PG8_BAR; PG8_SCHED;
;             PG8_LDA(At, 0, 1); PG8_STAGE(PG8_SB(0, 0), b2, voffB); PG8_STAGE(PG8_SB(0, 1), b2 + hstepB, voffB); PG8_STAGE(PG8_SA(0, 0), a2, voffA);
;             PG8_WAIT_V(8); PG8_WAIT_L(0); PG8_BAR; PG8_MMA(1, 0, At, B0); PG8_MMA(1, 1, At, B1); PG8_BAR; PG8_SCHED;
.Lprio_dn_697:
	s_waitcnt lgkmcnt(0)
	v_mfma_f32_16x16x32_bf16 v[124:127], v[152:155], v[188:191], 0
	v_mfma_f32_16x16x32_bf16 v[120:123], v[160:163], v[188:191], 0
	v_mfma_f32_16x16x32_bf16 v[116:119], v[152:155], v[196:199], 0
	v_mfma_f32_16x16x32_bf16 v[112:115], v[160:163], v[196:199], 0
	v_mfma_f32_16x16x32_bf16 v[100:103], v[152:155], v[204:207], 0
	v_mfma_f32_16x16x32_bf16 v[96:99], v[160:163], v[204:207], 0
	v_mfma_f32_16x16x32_bf16 v[84:87], v[152:155], v[212:215], 0
	v_mfma_f32_16x16x32_bf16 v[80:83], v[160:163], v[212:215], 0
	v_mfma_f32_16x16x32_bf16 v[124:127], v[156:159], v[192:195], v[124:127]
	v_mfma_f32_16x16x32_bf16 v[120:123], v[164:167], v[192:195], v[120:123]
	v_mfma_f32_16x16x32_bf16 v[116:119], v[156:159], v[200:203], v[116:119]
	v_mfma_f32_16x16x32_bf16 v[112:115], v[164:167], v[200:203], v[112:115]
	v_mfma_f32_16x16x32_bf16 v[100:103], v[156:159], v[208:211], v[100:103]
	v_mfma_f32_16x16x32_bf16 v[96:99], v[164:167], v[208:211], v[96:99]
	v_mfma_f32_16x16x32_bf16 v[84:87], v[156:159], v[216:219], v[84:87]
	v_mfma_f32_16x16x32_bf16 v[80:83], v[164:167], v[216:219], v[80:83]
	v_mfma_f32_16x16x32_bf16 v[108:111], v[168:171], v[188:191], 0
	v_mfma_f32_16x16x32_bf16 v[104:107], v[180:183], v[188:191], 0
	v_mfma_f32_16x16x32_bf16 v[92:95], v[168:171], v[196:199], 0
	v_mfma_f32_16x16x32_bf16 v[88:91], v[180:183], v[196:199], 0
	v_mfma_f32_16x16x32_bf16 v[76:79], v[168:171], v[204:207], 0
	v_mfma_f32_16x16x32_bf16 v[72:75], v[180:183], v[204:207], 0
	v_mfma_f32_16x16x32_bf16 v[68:71], v[168:171], v[212:215], 0
	v_mfma_f32_16x16x32_bf16 v[64:67], v[180:183], v[212:215], 0
	v_mfma_f32_16x16x32_bf16 v[108:111], v[172:175], v[192:195], v[108:111]
	v_mfma_f32_16x16x32_bf16 v[104:107], v[184:187], v[192:195], v[104:107]
	v_mfma_f32_16x16x32_bf16 v[92:95], v[172:175], v[200:203], v[92:95]
	v_mfma_f32_16x16x32_bf16 v[88:91], v[184:187], v[200:203], v[88:91]
	v_mfma_f32_16x16x32_bf16 v[76:79], v[172:175], v[208:211], v[76:79]
	v_mfma_f32_16x16x32_bf16 v[72:75], v[184:187], v[208:211], v[72:75]
	v_mfma_f32_16x16x32_bf16 v[68:71], v[172:175], v[216:219], v[68:71]
	v_mfma_f32_16x16x32_bf16 v[64:67], v[184:187], v[216:219], v[64:67]
	s_barrier
	s_mov_b32 m0, s87
	v_lshl_add_u64 v[220:221], s[50:51], 0, v[176:177]
	ds_read_b128 v[188:191], v139 offset:16384
	ds_read_b128 v[192:195], v139 offset:17408
	ds_read_b128 v[196:199], v139 offset:18432
	ds_read_b128 v[200:203], v139 offset:19456
	ds_read_b128 v[204:207], v139 offset:20480
	ds_read_b128 v[208:211], v139 offset:21504
	ds_read_b128 v[212:215], v139 offset:22528
	ds_read_b128 v[216:219], v139 offset:23552
	global_load_lds_dwordx4 v[220:221], off
	v_lshl_add_u64 v[222:223], s[50:51], 0, v[128:129]
	s_mov_b32 m0, s80
	v_lshl_add_u64 v[224:225], s[96:97], 0, v[176:177]
	global_load_lds_dwordx4 v[222:223], off
	s_mov_b32 m0, s86
	v_lshl_add_u64 v[226:227], s[96:97], 0, v[128:129]
	global_load_lds_dwordx4 v[224:225], off
	s_mov_b32 m0, s81
	v_lshl_add_u64 v[228:229], s[94:95], 0, v[132:133]
	global_load_lds_dwordx4 v[226:227], off
	s_mov_b32 m0, s16
	v_lshl_add_u64 v[230:231], s[94:95], 0, v[130:131]
	global_load_lds_dwordx4 v[228:229], off
	s_mov_b32 m0, s6
	s_nop 0
	global_load_lds_dwordx4 v[230:231], off
	s_waitcnt vmcnt(8)
	s_waitcnt lgkmcnt(0)
	s_barrier
	s_waitcnt lgkmcnt(0)
	v_mfma_f32_16x16x32_bf16 v[60:63], v[152:155], v[188:191], 0
	v_mfma_f32_16x16x32_bf16 v[56:59], v[160:163], v[188:191], 0
	v_mfma_f32_16x16x32_bf16 v[52:55], v[152:155], v[196:199], 0
	v_mfma_f32_16x16x32_bf16 v[48:51], v[160:163], v[196:199], 0
	v_mfma_f32_16x16x32_bf16 v[36:39], v[152:155], v[204:207], 0
	v_mfma_f32_16x16x32_bf16 v[32:35], v[160:163], v[204:207], 0
	v_mfma_f32_16x16x32_bf16 v[20:23], v[152:155], v[212:215], 0
	v_mfma_f32_16x16x32_bf16 v[16:19], v[160:163], v[212:215], 0
	v_mfma_f32_16x16x32_bf16 v[60:63], v[156:159], v[192:195], v[60:63]
	v_mfma_f32_16x16x32_bf16 v[56:59], v[164:167], v[192:195], v[56:59]
	v_mfma_f32_16x16x32_bf16 v[52:55], v[156:159], v[200:203], v[52:55]
	v_mfma_f32_16x16x32_bf16 v[48:51], v[164:167], v[200:203], v[48:51]
	v_mfma_f32_16x16x32_bf16 v[36:39], v[156:159], v[208:211], v[36:39]
	v_mfma_f32_16x16x32_bf16 v[32:35], v[164:167], v[208:211], v[32:35]
	v_mfma_f32_16x16x32_bf16 v[20:23], v[156:159], v[216:219], v[20:23]
	v_mfma_f32_16x16x32_bf16 v[16:19], v[164:167], v[216:219], v[16:19]
	v_mfma_f32_16x16x32_bf16 v[44:47], v[168:171], v[188:191], 0
	v_mfma_f32_16x16x32_bf16 v[40:43], v[180:183], v[188:191], 0
	v_mfma_f32_16x16x32_bf16 v[28:31], v[168:171], v[196:199], 0
	v_mfma_f32_16x16x32_bf16 v[24:27], v[180:183], v[196:199], 0
	v_mfma_f32_16x16x32_bf16 v[12:15], v[168:171], v[204:207], 0
	v_mfma_f32_16x16x32_bf16 v[8:11], v[180:183], v[204:207], 0
	v_mfma_f32_16x16x32_bf16 v[4:7], v[168:171], v[212:215], 0
	v_mfma_f32_16x16x32_bf16 v[0:3], v[180:183], v[212:215], 0
	v_mfma_f32_16x16x32_bf16 v[44:47], v[172:175], v[192:195], v[44:47]
	v_mfma_f32_16x16x32_bf16 v[40:43], v[184:187], v[192:195], v[40:43]
	v_mfma_f32_16x16x32_bf16 v[28:31], v[172:175], v[200:203], v[28:31]
	v_mfma_f32_16x16x32_bf16 v[24:27], v[184:187], v[200:203], v[24:27]
	v_mfma_f32_16x16x32_bf16 v[12:15], v[172:175], v[208:211], v[12:15]
	v_mfma_f32_16x16x32_bf16 v[8:11], v[184:187], v[208:211], v[8:11]
	v_mfma_f32_16x16x32_bf16 v[4:7], v[172:175], v[216:219], v[4:7]
	v_mfma_f32_16x16x32_bf16 v[0:3], v[184:187], v[216:219], v[0:3]
	s_barrier
	s_branch .Lgemm_join_697

; #define PG8_STAGE(bufoff, gbase, voff) do { _Pragma("unroll") for (int _i = 0; _i < 2; ++_i) \
;         __builtin_amdgcn_global_load_lds((const unsigned*)((const char*)(gbase) + (voff)[_i]), (LAS unsigned*)(lds + (bufoff) + ldsw + _i * 8192), 16, 0, 0); } while (0)
; #define PG8_LDA(dst, b, h) do { _Pragma("unroll") for (int m = 0; m < 4; ++m) _Pragma("unroll") for (int k = 0; k < 2; ++k) dst[m][k] = *(const LAS bf16x8*)(lds + PG8_SA(b, h) + aoff + m * 2048 + k * 1024); } while (0)
; #define PG8_LDB(dst, b, h) do { _Pragma("unroll") for (int n = 0; n < 2; ++n) _Pragma("unroll") for (int k = 0; k < 2; ++k) dst[n][k] = *(const LAS bf16x8*)(lds + PG8_SB(b, h) + boff + n * 2048 + k * 1024); } while (0)
; #define PG8_MMA(ai, bj, At, Bt) do { __builtin_amdgcn_s_setprio(1); _Pragma("unroll") for (int m = 0; m < 4; ++m) _Pragma("unroll") for (int n = 0; n < 2; ++n) _Pragma("unroll") for (int k = 0; k < 2; ++k) \
;         acc[ai][bj][m][n] = __builtin_amdgcn_mfma_f32_16x16x32_bf16(Bt[n][k], At[m][k], acc[ai][bj][m][n], 0, 0, 0); __builtin_amdgcn_s_setprio(0); } while (0)
; #define PG8_WAIT_V(n) asm volatile("s_waitcnt vmcnt(" #n ")" ::: "memory")
; #define PG8_WAIT_L(n) asm volatile("s_waitcnt lgkmcnt(" #n ")" ::: "memory")
; template <class Epi, class Sched, bool ALIGN_EPI>
; __device__ __forceinline__ void gemm_phase(LAS unsigned char* lds, const int wid, const int lda_, const int ldb_, const int K_, const Sched& S, const Epi& E) {
;     ...
;         const bool has_next = S.next(ui + 1, nxt);
;         const int nt = S.nt(cur);
;         const char* nA = has_next ? S.a(nxt) : cA; const char* nB = has_next ? S.b(nxt) : cB;
; #pragma unroll 1
;         for (int t = 0; t < nt; t += 2) {
;             const bool last = (t == nt - 2);
;             const char* a1 = cA + (size_t)(t + 1) * kstep;
;             const char* a2 = last ? nA : cA + (size_t)(t + 2) * kstep; const char* b2 = last ? nB : cB + (size_t)(t + 2) * kstep;
;             const char* a3 = a2 + kstep; const char* b3 = b2 + kstep;
;             PG8_LDB(B0, 0, 0); PG8_LDB(B1, 0, 1); PG8_SCHED; PG8_LDA(At, 0, 0); PG8_STAGE(PG8_SA(1, 1), a1 + hstepA, voffA);
;             PG8_WAIT_V(8); PG8_WAIT_L(0); PG8_BAR; PG8_MMA(0, 0, At, B0); PG8_MMA(0, 1, At, B1); PG8_BAR; PG8_SCHED;
;     __device__ __forceinline__ const char* a(const pg8::Unit& u) const { return (const char*)ws + (u.pm < 64 ? WS_W2 : WS_W2C); }
.LBB0_882:
	s_and_b64 s[4:5], s[4:5], exec
	s_cselect_b32 s4, s27, 0x380000
	s_add_u32 s44, s66, s4
	s_addc_u32 s45, s67, 0
	s_and_b64 s[4:5], s[50:51], exec
	s_cselect_b32 s4, s45, s47
	s_cselect_b32 s5, s44, s46
	s_add_u32 s42, s46, 0x80
	s_addc_u32 s43, s47, 0
	s_add_u32 s31, s48, 0x100
	v_lshl_add_u64 v[156:157], s[42:43], 0, v[152:153]
	v_lshl_add_u64 v[158:159], s[42:43], 0, v[154:155]
	s_addc_u32 s35, s49, 0
	s_mov_b32 s73, -2
	s_mov_b64 s[48:49], 0
	s_add_u32 s17, s46, s48
	s_addc_u32 s27, s47, s49
	s_add_u32 s17, s17, 0x100
	s_addc_u32 s27, s27, 0
	s_add_u32 s42, s31, s48
	s_addc_u32 s43, s35, s49
	s_add_i32 s74, 0, 0x10000
	s_cmpk_eq_i32 s48, 0x300
	s_cselect_b32 s51, s4, s27
	s_cselect_b32 s50, s5, s17
	v_add_u32_e32 v141, s74, v135
	s_cselect_b32 s43, s39, s43
	s_cselect_b32 s42, s38, s42
	s_add_i32 s17, 0, 0x14000
	ds_read_b128 v[160:163], v141
	ds_read_b128 v[164:167], v141 offset:1024
	ds_read_b128 v[168:171], v141 offset:2048
	ds_read_b128 v[172:175], v141 offset:3072
	v_add_u32_e32 v141, s17, v135
	ds_read_b128 v[180:183], v141
	ds_read_b128 v[184:187], v141 offset:1024
	ds_read_b128 v[188:191], v141 offset:2048
	ds_read_b128 v[192:195], v141 offset:3072
	v_lshl_add_u64 v[228:229], v[158:159], 0, s[48:49]
	s_add_i32 m0, s16, 0xc000
	ds_read_b128 v[196:199], v139
	ds_read_b128 v[200:203], v139 offset:1024
	ds_read_b128 v[204:207], v139 offset:2048
	ds_read_b128 v[208:211], v139 offset:3072
	ds_read_b128 v[212:215], v139 offset:4096
	ds_read_b128 v[216:219], v139 offset:5120
	ds_read_b128 v[220:223], v139 offset:6144
	ds_read_b128 v[224:227], v139 offset:7168
	global_load_lds_dwordx4 v[228:229], off
	v_lshl_add_u64 v[228:229], v[156:157], 0, s[48:49]
	s_add_i32 m0, s16, 0xe000
	s_nop 0
	global_load_lds_dwordx4 v[228:229], off
	s_waitcnt vmcnt(8)
	s_waitcnt lgkmcnt(0)
	s_barrier
	v_readlane_b32 s101, v252, 58
	s_setprio 0
	s_cmp_eq_u32 s101, 0
	s_cbranch_scc1 .Lprio_dn_883
	s_setprio 1
; #define PG8_STAGE(bufoff, gbase, voff) do { _Pragma("unroll") for (int _i = 0; _i < 2; ++_i) \
;         __builtin_amdgcn_global_load_lds((const unsigned*)((const char*)(gbase) + (voff)[_i]), (LAS unsigned*)(lds + (bufoff) + ldsw + _i * 8192), 16, 0, 0); } while (0)
; #define PG8_LDA(dst, b, h) do { _Pragma("unroll") for (int m = 0; m < 4; ++m) _Pragma("unroll") for (int k = 0; k < 2; ++k) dst[m][k] = *(const LAS bf16x8*)(lds + PG8_SA(b, h) + aoff + m * 2048 + k * 1024); } while (0)
; #define PG8_MMA(ai, bj, At, Bt) do { __builtin_amdgcn_s_setprio(1); _Pragma("unroll") for (int m = 0; m < 4; ++m) _Pragma("unroll") for (int n = 0; n < 2; ++n) _Pragma("unroll") for (int k = 0; k < 2; ++k) \
;         acc[ai][bj][m][n] = __builtin_amdgcn_mfma_f32_16x16x32_bf16(Bt[n][k], At[m][k], acc[ai][bj][m][n], 0, 0, 0); __builtin_amdgcn_s_setprio(0); } while (0)
; #define PG8_WAIT_V(n) asm volatile("s_waitcnt vmcnt(" #n ")" ::: "memory")
; #define PG8_WAIT_L(n) asm volatile("s_waitcnt lgkmcnt(" #n ")" ::: "memory")
; #define PG8_BAR __builtin_amdgcn_s_barrier()
; #define PG8_SCHED __builtin_amdgcn_sched_barrier(0)
; template <class Epi, class Sched, bool ALIGN_EPI>
; __device__ __forceinline__ void gemm_phase(LAS unsigned char* lds, const int wid, const int lda_, const int ldb_, const int K_, const Sched& S, const Epi& E) {
;     ...
;             PG8_WAIT_V(8); PG8_WAIT_L(0); PG8_BAR; PG8_MMA(0, 0, At, B0); PG8_MMA(0, 1, At, B1); PG8_BAR; PG8_SCHED;
;             PG8_LDA(At, 0, 1); PG8_STAGE(PG8_SB(0, 0), b2, voffB); PG8_STAGE(PG8_SB(0, 1), b2 + hstepB, voffB); PG8_STAGE(PG8_SA(0, 0), a2, voffA);
;             PG8_WAIT_V(8); PG8_WAIT_L(0); PG8_BAR; PG8_MMA(1, 0, At, B0); PG8_MMA(1, 1, At, B1); PG8_BAR; PG8_SCHED;
.Lprio_dn_883:
	s_waitcnt lgkmcnt(0)
	v_mfma_f32_16x16x32_bf16 v[124:127], v[160:163], v[196:199], 0
	v_mfma_f32_16x16x32_bf16 v[120:123], v[168:171], v[196:199], 0
	v_mfma_f32_16x16x32_bf16 v[116:119], v[160:163], v[204:207], 0
	v_mfma_f32_16x16x32_bf16 v[112:115], v[168:171], v[204:207], 0
	v_mfma_f32_16x16x32_bf16 v[100:103], v[160:163], v[212:215], 0
	v_mfma_f32_16x16x32_bf16 v[96:99], v[168:171], v[212:215], 0
	v_mfma_f32_16x16x32_bf16 v[84:87], v[160:163], v[220:223], 0
	v_mfma_f32_16x16x32_bf16 v[80:83], v[168:171], v[220:223], 0
	v_mfma_f32_16x16x32_bf16 v[124:127], v[164:167], v[200:203], v[124:127]
	v_mfma_f32_16x16x32_bf16 v[120:123], v[172:175], v[200:203], v[120:123]
	v_mfma_f32_16x16x32_bf16 v[116:119], v[164:167], v[208:211], v[116:119]
	v_mfma_f32_16x16x32_bf16 v[112:115], v[172:175], v[208:211], v[112:115]
	v_mfma_f32_16x16x32_bf16 v[100:103], v[164:167], v[216:219], v[100:103]
	v_mfma_f32_16x16x32_bf16 v[96:99], v[172:175], v[216:219], v[96:99]
	v_mfma_f32_16x16x32_bf16 v[84:87], v[164:167], v[224:227], v[84:87]
	v_mfma_f32_16x16x32_bf16 v[80:83], v[172:175], v[224:227], v[80:83]
	v_mfma_f32_16x16x32_bf16 v[108:111], v[180:183], v[196:199], 0
	v_mfma_f32_16x16x32_bf16 v[104:107], v[188:191], v[196:199], 0
	v_mfma_f32_16x16x32_bf16 v[92:95], v[180:183], v[204:207], 0
	v_mfma_f32_16x16x32_bf16 v[88:91], v[188:191], v[204:207], 0
	v_mfma_f32_16x16x32_bf16 v[76:79], v[180:183], v[212:215], 0
	v_mfma_f32_16x16x32_bf16 v[72:75], v[188:191], v[212:215], 0
	v_mfma_f32_16x16x32_bf16 v[68:71], v[180:183], v[220:223], 0
	v_mfma_f32_16x16x32_bf16 v[64:67], v[188:191], v[220:223], 0
	v_mfma_f32_16x16x32_bf16 v[108:111], v[184:187], v[200:203], v[108:111]
	v_mfma_f32_16x16x32_bf16 v[104:107], v[192:195], v[200:203], v[104:107]
	v_mfma_f32_16x16x32_bf16 v[92:95], v[184:187], v[208:211], v[92:95]
	v_mfma_f32_16x16x32_bf16 v[88:91], v[192:195], v[208:211], v[88:91]
	v_mfma_f32_16x16x32_bf16 v[76:79], v[184:187], v[216:219], v[76:79]
	v_mfma_f32_16x16x32_bf16 v[72:75], v[192:195], v[216:219], v[72:75]
	v_mfma_f32_16x16x32_bf16 v[68:71], v[184:187], v[224:227], v[68:71]
	v_mfma_f32_16x16x32_bf16 v[64:67], v[192:195], v[224:227], v[64:67]
	s_barrier
	s_add_i32 s27, s74, s3
	v_lshl_add_u64 v[228:229], s[42:43], 0, v[176:177]
	s_mov_b32 m0, s27
	ds_read_b128 v[196:199], v139 offset:16384
	ds_read_b128 v[200:203], v139 offset:17408
	ds_read_b128 v[204:207], v139 offset:18432
	ds_read_b128 v[208:211], v139 offset:19456
	ds_read_b128 v[212:215], v139 offset:20480
	ds_read_b128 v[216:219], v139 offset:21504
	ds_read_b128 v[220:223], v139 offset:22528
	ds_read_b128 v[224:227], v139 offset:23552
	global_load_lds_dwordx4 v[228:229], off
	s_add_i32 m0, s27, 0x2000
	v_lshl_add_u64 v[230:231], s[42:43], 0, v[132:133]
	s_add_u32 s42, s42, s10
	s_addc_u32 s43, s43, s11
	s_add_i32 s17, s17, s3
	global_load_lds_dwordx4 v[230:231], off
	v_lshl_add_u64 v[232:233], s[42:43], 0, v[176:177]
	s_mov_b32 m0, s17
	v_lshl_add_u64 v[234:235], s[42:43], 0, v[132:133]
	global_load_lds_dwordx4 v[232:233], off
	s_add_i32 m0, s17, 0x2000
	v_lshl_add_u64 v[236:237], s[50:51], 0, v[128:129]
	global_load_lds_dwordx4 v[234:235], off
	s_mov_b32 m0, s16
	v_lshl_add_u64 v[246:247], s[50:51], 0, v[130:131]
	global_load_lds_dwordx4 v[236:237], off
	s_mov_b32 m0, s6
	s_nop 0
	global_load_lds_dwordx4 v[246:247], off
	s_waitcnt vmcnt(8)
	s_waitcnt lgkmcnt(0)
	s_barrier
	s_waitcnt lgkmcnt(0)
	v_mfma_f32_16x16x32_bf16 v[60:63], v[160:163], v[196:199], 0
	v_mfma_f32_16x16x32_bf16 v[56:59], v[168:171], v[196:199], 0
	v_mfma_f32_16x16x32_bf16 v[52:55], v[160:163], v[204:207], 0
	v_mfma_f32_16x16x32_bf16 v[48:51], v[168:171], v[204:207], 0
	v_mfma_f32_16x16x32_bf16 v[36:39], v[160:163], v[212:215], 0
	v_mfma_f32_16x16x32_bf16 v[32:35], v[168:171], v[212:215], 0
	v_mfma_f32_16x16x32_bf16 v[20:23], v[160:163], v[220:223], 0
	v_mfma_f32_16x16x32_bf16 v[16:19], v[168:171], v[220:223], 0
	v_mfma_f32_16x16x32_bf16 v[60:63], v[164:167], v[200:203], v[60:63]
	v_mfma_f32_16x16x32_bf16 v[56:59], v[172:175], v[200:203], v[56:59]
	v_mfma_f32_16x16x32_bf16 v[52:55], v[164:167], v[208:211], v[52:55]
	v_mfma_f32_16x16x32_bf16 v[48:51], v[172:175], v[208:211], v[48:51]
	v_mfma_f32_16x16x32_bf16 v[36:39], v[164:167], v[216:219], v[36:39]
	v_mfma_f32_16x16x32_bf16 v[32:35], v[172:175], v[216:219], v[32:35]
	v_mfma_f32_16x16x32_bf16 v[20:23], v[164:167], v[224:227], v[20:23]
	v_mfma_f32_16x16x32_bf16 v[16:19], v[172:175], v[224:227], v[16:19]
	v_mfma_f32_16x16x32_bf16 v[44:47], v[180:183], v[196:199], 0
	v_mfma_f32_16x16x32_bf16 v[40:43], v[188:191], v[196:199], 0
	v_mfma_f32_16x16x32_bf16 v[28:31], v[180:183], v[204:207], 0
	v_mfma_f32_16x16x32_bf16 v[24:27], v[188:191], v[204:207], 0
	v_mfma_f32_16x16x32_bf16 v[12:15], v[180:183], v[212:215], 0
	v_mfma_f32_16x16x32_bf16 v[8:11], v[188:191], v[212:215], 0
	v_mfma_f32_16x16x32_bf16 v[4:7], v[180:183], v[220:223], 0
	v_mfma_f32_16x16x32_bf16 v[0:3], v[188:191], v[220:223], 0
	v_mfma_f32_16x16x32_bf16 v[44:47], v[184:187], v[200:203], v[44:47]
	v_mfma_f32_16x16x32_bf16 v[40:43], v[192:195], v[200:203], v[40:43]
	v_mfma_f32_16x16x32_bf16 v[28:31], v[184:187], v[208:211], v[28:31]
	v_mfma_f32_16x16x32_bf16 v[24:27], v[192:195], v[208:211], v[24:27]
	v_mfma_f32_16x16x32_bf16 v[12:15], v[184:187], v[216:219], v[12:15]
	v_mfma_f32_16x16x32_bf16 v[8:11], v[192:195], v[216:219], v[8:11]
	v_mfma_f32_16x16x32_bf16 v[4:7], v[184:187], v[224:227], v[4:7]
	v_mfma_f32_16x16x32_bf16 v[0:3], v[192:195], v[224:227], v[0:3]
	s_barrier
	s_branch .Lgemm_join_883

; #define PG8_STAGE(bufoff, gbase, voff) do { _Pragma("unroll") for (int _i = 0; _i < 2; ++_i) \
;         __builtin_amdgcn_global_load_lds((const unsigned*)((const char*)(gbase) + (voff)[_i]), (LAS unsigned*)(lds + (bufoff) + ldsw + _i * 8192), 16, 0, 0); } while (0)
; #define PG8_LDA(dst, b, h) do { _Pragma("unroll") for (int m = 0; m < 4; ++m) _Pragma("unroll") for (int k = 0; k < 2; ++k) dst[m][k] = *(const LAS bf16x8*)(lds + PG8_SA(b, h) + aoff + m * 2048 + k * 1024); } while (0)
; #define PG8_LDB(dst, b, h) do { _Pragma("unroll") for (int n = 0; n < 2; ++n) _Pragma("unroll") for (int k = 0; k < 2; ++k) dst[n][k] = *(const LAS bf16x8*)(lds + PG8_SB(b, h) + boff + n * 2048 + k * 1024); } while (0)
; #define PG8_MMA(ai, bj, At, Bt) do { __builtin_amdgcn_s_setprio(1); _Pragma("unroll") for (int m = 0; m < 4; ++m) _Pragma("unroll") for (int n = 0; n < 2; ++n) _Pragma("unroll") for (int k = 0; k < 2; ++k) \
;         acc[ai][bj][m][n] = __builtin_amdgcn_mfma_f32_16x16x32_bf16(Bt[n][k], At[m][k], acc[ai][bj][m][n], 0, 0, 0); __builtin_amdgcn_s_setprio(0); } while (0)
; #define PG8_WAIT_V(n) asm volatile("s_waitcnt vmcnt(" #n ")" ::: "memory")
; #define PG8_WAIT_L(n) asm volatile("s_waitcnt lgkmcnt(" #n ")" ::: "memory")
; #define PG8_BAR __builtin_amdgcn_s_barrier()
; #define PG8_SCHED __builtin_amdgcn_sched_barrier(0)
; template <class Epi, class Sched, bool ALIGN_EPI>
; __device__ __forceinline__ void gemm_phase(LAS unsigned char* lds, const int wid, const int lda_, const int ldb_, const int K_, const Sched& S, const Epi& E) {
;     ...
;         const bool has_next = S.next(ui + 1, nxt);
;         const int nt = S.nt(cur);
;         const char* nA = has_next ? S.a(nxt) : cA; const char* nB = has_next ? S.b(nxt) : cB;
; #pragma unroll 1
;         for (int t = 0; t < nt; t += 2) {
;             const bool last = (t == nt - 2);
;             const char* a1 = cA + (size_t)(t + 1) * kstep;
;             const char* a2 = last ? nA : cA + (size_t)(t + 2) * kstep; const char* b2 = last ? nB : cB + (size_t)(t + 2) * kstep;
;             const char* a3 = a2 + kstep; const char* b3 = b2 + kstep;
;             PG8_LDB(B0, 0, 0); PG8_LDB(B1, 0, 1); PG8_SCHED; PG8_LDA(At, 0, 0); PG8_STAGE(PG8_SA(1, 1), a1 + hstepA, voffA);
;             PG8_WAIT_V(8); PG8_WAIT_L(0); PG8_BAR; PG8_MMA(0, 0, At, B0); PG8_MMA(0, 1, At, B1); PG8_BAR; PG8_SCHED;
.LBB0_961:
	s_xor_b64 s[36:37], s[4:5], -1
	s_cmp_gt_i32 s48, -1
	s_cselect_b64 s[50:51], -1, 0
	s_cmp_lt_i32 s48, 0
	s_cselect_b32 s45, 32, 8
	s_max_i32 s17, s75, 0
	s_ashr_i32 s35, s34, 31
	s_lshl_b32 s17, s17, 10
	s_lshl_b64 s[38:39], s[34:35], 20
	v_readlane_b32 s27, v254, 19
	s_add_u32 s27, s27, s38
	v_readlane_b32 s31, v254, 20
	s_addc_u32 s31, s31, s39
	s_add_u32 s38, s27, s17
	s_addc_u32 s39, s31, 0
	s_and_b64 s[40:41], s[4:5], exec
	s_cselect_b32 s35, s39, s95
	s_cselect_b32 s47, s38, s94
	s_ashr_i32 s31, s30, 31
	s_lshl_b64 s[40:41], s[30:31], 20
	s_add_u32 s27, s6, s40
	s_addc_u32 s31, s7, s41
	s_add_u32 s40, s27, s17
	s_addc_u32 s41, s31, 0
	s_and_b64 s[4:5], s[4:5], exec
	s_cselect_b32 s4, s41, s97
	s_cselect_b32 s5, s40, s96
	s_add_i32 s31, s45, -2
	s_add_u32 s94, s94, 0x80
	s_addc_u32 s95, s95, 0
	s_add_u32 s49, s96, 0x100
	s_mov_b32 s77, 0
	s_addc_u32 s76, s97, 0
	s_add_i32 s78, s77, 2
	s_add_u32 s17, s94, 0x80
	s_addc_u32 s27, s95, 0
	s_add_i32 s79, 0, 0x10000
	s_cmp_eq_u32 s31, s77
	s_cselect_b32 s97, s35, s27
	s_cselect_b32 s96, s47, s17
	v_add_u32_e32 v141, s79, v135
	s_cselect_b32 s43, s4, s76
	s_cselect_b32 s42, s5, s49
	s_add_i32 s17, 0, 0x14000
	ds_read_b128 v[156:159], v141
	ds_read_b128 v[160:163], v141 offset:1024
	ds_read_b128 v[164:167], v141 offset:2048
	ds_read_b128 v[168:171], v141 offset:3072
	v_add_u32_e32 v141, s17, v135
	ds_read_b128 v[172:175], v141
	ds_read_b128 v[180:183], v141 offset:1024
	ds_read_b128 v[184:187], v141 offset:2048
	ds_read_b128 v[188:191], v141 offset:3072
	v_lshl_add_u64 v[224:225], s[94:95], 0, v[152:153]
	s_add_i32 m0, s16, 0xc000
	ds_read_b128 v[192:195], v139
	ds_read_b128 v[196:199], v139 offset:1024
	ds_read_b128 v[200:203], v139 offset:2048
	ds_read_b128 v[204:207], v139 offset:3072
	ds_read_b128 v[208:211], v139 offset:4096
	ds_read_b128 v[212:215], v139 offset:5120
	ds_read_b128 v[216:219], v139 offset:6144
	ds_read_b128 v[220:223], v139 offset:7168
	global_load_lds_dwordx4 v[224:225], off
	v_lshl_add_u64 v[224:225], s[94:95], 0, v[154:155]
	s_add_i32 m0, s16, 0xe000
	s_nop 0
	global_load_lds_dwordx4 v[224:225], off
	s_waitcnt vmcnt(8)
	s_waitcnt lgkmcnt(0)
	s_barrier
	v_readlane_b32 s101, v252, 58
	s_setprio 0
	s_cmp_eq_u32 s101, 0
	s_cbranch_scc1 .Lprio_dn_962
	s_setprio 1
; #define PG8_STAGE(bufoff, gbase, voff) do { _Pragma("unroll") for (int _i = 0; _i < 2; ++_i) \
;         __builtin_amdgcn_global_load_lds((const unsigned*)((const char*)(gbase) + (voff)[_i]), (LAS unsigned*)(lds + (bufoff) + ldsw + _i * 8192), 16, 0, 0); } while (0)
; #define PG8_LDA(dst, b, h) do { _Pragma("unroll") for (int m = 0; m < 4; ++m) _Pragma("unroll") for (int k = 0; k < 2; ++k) dst[m][k] = *(const LAS bf16x8*)(lds + PG8_SA(b, h) + aoff + m * 2048 + k * 1024); } while (0)
; #define PG8_MMA(ai, bj, At, Bt) do { __builtin_amdgcn_s_setprio(1); _Pragma("unroll") for (int m = 0; m < 4; ++m) _Pragma("unroll") for (int n = 0; n < 2; ++n) _Pragma("unroll") for (int k = 0; k < 2; ++k) \
;         acc[ai][bj][m][n] = __builtin_amdgcn_mfma_f32_16x16x32_bf16(Bt[n][k], At[m][k], acc[ai][bj][m][n], 0, 0, 0); __builtin_amdgcn_s_setprio(0); } while (0)
; #define PG8_WAIT_V(n) asm volatile("s_waitcnt vmcnt(" #n ")" ::: "memory")
; #define PG8_WAIT_L(n) asm volatile("s_waitcnt lgkmcnt(" #n ")" ::: "memory")
; #define PG8_BAR __builtin_amdgcn_s_barrier()
; #define PG8_SCHED __builtin_amdgcn_sched_barrier(0)
; template <class Epi, class Sched, bool ALIGN_EPI>
; __device__ __forceinline__ void gemm_phase(LAS unsigned char* lds, const int wid, const int lda_, const int ldb_, const int K_, const Sched& S, const Epi& E) {
;     ...
;             PG8_WAIT_V(8); PG8_WAIT_L(0); PG8_BAR; PG8_MMA(0, 0, At, B0); PG8_MMA(0, 1, At, B1); PG8_BAR; PG8_SCHED;
;             PG8_LDA(At, 0, 1); PG8_STAGE(PG8_SB(0, 0), b2, voffB); PG8_STAGE(PG8_SB(0, 1), b2 + hstepB, voffB); PG8_STAGE(PG8_SA(0, 0), a2, voffA);
;             PG8_WAIT_V(8); PG8_WAIT_L(0); PG8_BAR; PG8_MMA(1, 0, At, B0); PG8_MMA(1, 1, At, B1); PG8_BAR; PG8_SCHED;
.Lprio_dn_962:
	s_waitcnt lgkmcnt(0)
	v_mfma_f32_16x16x32_bf16 v[124:127], v[156:159], v[192:195], 0
	v_mfma_f32_16x16x32_bf16 v[120:123], v[164:167], v[192:195], 0
	v_mfma_f32_16x16x32_bf16 v[116:119], v[156:159], v[200:203], 0
	v_mfma_f32_16x16x32_bf16 v[112:115], v[164:167], v[200:203], 0
	v_mfma_f32_16x16x32_bf16 v[100:103], v[156:159], v[208:211], 0
	v_mfma_f32_16x16x32_bf16 v[96:99], v[164:167], v[208:211], 0
	v_mfma_f32_16x16x32_bf16 v[84:87], v[156:159], v[216:219], 0
	v_mfma_f32_16x16x32_bf16 v[80:83], v[164:167], v[216:219], 0
	v_mfma_f32_16x16x32_bf16 v[124:127], v[160:163], v[196:199], v[124:127]
	v_mfma_f32_16x16x32_bf16 v[120:123], v[168:171], v[196:199], v[120:123]
	v_mfma_f32_16x16x32_bf16 v[116:119], v[160:163], v[204:207], v[116:119]
	v_mfma_f32_16x16x32_bf16 v[112:115], v[168:171], v[204:207], v[112:115]
	v_mfma_f32_16x16x32_bf16 v[100:103], v[160:163], v[212:215], v[100:103]
	v_mfma_f32_16x16x32_bf16 v[96:99], v[168:171], v[212:215], v[96:99]
	v_mfma_f32_16x16x32_bf16 v[84:87], v[160:163], v[220:223], v[84:87]
	v_mfma_f32_16x16x32_bf16 v[80:83], v[168:171], v[220:223], v[80:83]
	v_mfma_f32_16x16x32_bf16 v[108:111], v[172:175], v[192:195], 0
	v_mfma_f32_16x16x32_bf16 v[104:107], v[184:187], v[192:195], 0
	v_mfma_f32_16x16x32_bf16 v[92:95], v[172:175], v[200:203], 0
	v_mfma_f32_16x16x32_bf16 v[88:91], v[184:187], v[200:203], 0
	v_mfma_f32_16x16x32_bf16 v[76:79], v[172:175], v[208:211], 0
	v_mfma_f32_16x16x32_bf16 v[72:75], v[184:187], v[208:211], 0
	v_mfma_f32_16x16x32_bf16 v[68:71], v[172:175], v[216:219], 0
	v_mfma_f32_16x16x32_bf16 v[64:67], v[184:187], v[216:219], 0
	v_mfma_f32_16x16x32_bf16 v[108:111], v[180:183], v[196:199], v[108:111]
	v_mfma_f32_16x16x32_bf16 v[104:107], v[188:191], v[196:199], v[104:107]
	v_mfma_f32_16x16x32_bf16 v[92:95], v[180:183], v[204:207], v[92:95]
	v_mfma_f32_16x16x32_bf16 v[88:91], v[188:191], v[204:207], v[88:91]
	v_mfma_f32_16x16x32_bf16 v[76:79], v[180:183], v[212:215], v[76:79]
	v_mfma_f32_16x16x32_bf16 v[72:75], v[188:191], v[212:215], v[72:75]
	v_mfma_f32_16x16x32_bf16 v[68:71], v[180:183], v[220:223], v[68:71]
	v_mfma_f32_16x16x32_bf16 v[64:67], v[188:191], v[220:223], v[64:67]
	s_barrier
	s_add_i32 s27, s79, s3
	v_lshl_add_u64 v[224:225], s[42:43], 0, v[176:177]
	s_mov_b32 m0, s27
	ds_read_b128 v[192:195], v139 offset:16384
	ds_read_b128 v[196:199], v139 offset:17408
	ds_read_b128 v[200:203], v139 offset:18432
	ds_read_b128 v[204:207], v139 offset:19456
	ds_read_b128 v[208:211], v139 offset:20480
	ds_read_b128 v[212:215], v139 offset:21504
	ds_read_b128 v[216:219], v139 offset:22528
	ds_read_b128 v[220:223], v139 offset:23552
	global_load_lds_dwordx4 v[224:225], off
	s_add_i32 m0, s27, 0x2000
	v_lshl_add_u64 v[226:227], s[42:43], 0, v[128:129]
	s_add_u32 s42, s42, s10
	s_addc_u32 s43, s43, s11
	s_add_i32 s17, s17, s3
	global_load_lds_dwordx4 v[226:227], off
	v_lshl_add_u64 v[228:229], s[42:43], 0, v[176:177]
	s_mov_b32 m0, s17
	v_lshl_add_u64 v[230:231], s[42:43], 0, v[128:129]
	global_load_lds_dwordx4 v[228:229], off
	s_add_i32 m0, s17, 0x2000
	v_lshl_add_u64 v[232:233], s[96:97], 0, v[132:133]
	global_load_lds_dwordx4 v[230:231], off
	s_mov_b32 m0, s16
	v_lshl_add_u64 v[234:235], s[96:97], 0, v[130:131]
	global_load_lds_dwordx4 v[232:233], off
	s_mov_b32 m0, s14
	s_nop 0
	global_load_lds_dwordx4 v[234:235], off
	s_waitcnt vmcnt(8)
	s_waitcnt lgkmcnt(0)
	s_barrier
	s_waitcnt lgkmcnt(0)
	v_mfma_f32_16x16x32_bf16 v[60:63], v[156:159], v[192:195], 0
	v_mfma_f32_16x16x32_bf16 v[56:59], v[164:167], v[192:195], 0
	v_mfma_f32_16x16x32_bf16 v[52:55], v[156:159], v[200:203], 0
	v_mfma_f32_16x16x32_bf16 v[48:51], v[164:167], v[200:203], 0
	v_mfma_f32_16x16x32_bf16 v[36:39], v[156:159], v[208:211], 0
	v_mfma_f32_16x16x32_bf16 v[32:35], v[164:167], v[208:211], 0
	v_mfma_f32_16x16x32_bf16 v[20:23], v[156:159], v[216:219], 0
	v_mfma_f32_16x16x32_bf16 v[16:19], v[164:167], v[216:219], 0
	v_mfma_f32_16x16x32_bf16 v[60:63], v[160:163], v[196:199], v[60:63]
	v_mfma_f32_16x16x32_bf16 v[56:59], v[168:171], v[196:199], v[56:59]
	v_mfma_f32_16x16x32_bf16 v[52:55], v[160:163], v[204:207], v[52:55]
	v_mfma_f32_16x16x32_bf16 v[48:51], v[168:171], v[204:207], v[48:51]
	v_mfma_f32_16x16x32_bf16 v[36:39], v[160:163], v[212:215], v[36:39]
	v_mfma_f32_16x16x32_bf16 v[32:35], v[168:171], v[212:215], v[32:35]
	v_mfma_f32_16x16x32_bf16 v[20:23], v[160:163], v[220:223], v[20:23]
	v_mfma_f32_16x16x32_bf16 v[16:19], v[168:171], v[220:223], v[16:19]
	v_mfma_f32_16x16x32_bf16 v[44:47], v[172:175], v[192:195], 0
	v_mfma_f32_16x16x32_bf16 v[40:43], v[184:187], v[192:195], 0
	v_mfma_f32_16x16x32_bf16 v[28:31], v[172:175], v[200:203], 0
	v_mfma_f32_16x16x32_bf16 v[24:27], v[184:187], v[200:203], 0
	v_mfma_f32_16x16x32_bf16 v[12:15], v[172:175], v[208:211], 0
	v_mfma_f32_16x16x32_bf16 v[8:11], v[184:187], v[208:211], 0
	v_mfma_f32_16x16x32_bf16 v[4:7], v[172:175], v[216:219], 0
	v_mfma_f32_16x16x32_bf16 v[0:3], v[184:187], v[216:219], 0
	v_mfma_f32_16x16x32_bf16 v[44:47], v[180:183], v[196:199], v[44:47]
	v_mfma_f32_16x16x32_bf16 v[40:43], v[188:191], v[196:199], v[40:43]
	v_mfma_f32_16x16x32_bf16 v[28:31], v[180:183], v[204:207], v[28:31]
	v_mfma_f32_16x16x32_bf16 v[24:27], v[188:191], v[204:207], v[24:27]
	v_mfma_f32_16x16x32_bf16 v[12:15], v[180:183], v[212:215], v[12:15]
	v_mfma_f32_16x16x32_bf16 v[8:11], v[188:191], v[212:215], v[8:11]
	v_mfma_f32_16x16x32_bf16 v[4:7], v[180:183], v[220:223], v[4:7]
	v_mfma_f32_16x16x32_bf16 v[0:3], v[188:191], v[220:223], v[0:3]
	s_barrier
	s_branch .Lgemm_join_962

; #define PG8_STAGE(bufoff, gbase, voff) do { _Pragma("unroll") for (int _i = 0; _i < 2; ++_i) \
;         __builtin_amdgcn_global_load_lds((const unsigned*)((const char*)(gbase) + (voff)[_i]), (LAS unsigned*)(lds + (bufoff) + ldsw + _i * 8192), 16, 0, 0); } while (0)
; #define PG8_LDA(dst, b, h) do { _Pragma("unroll") for (int m = 0; m < 4; ++m) _Pragma("unroll") for (int k = 0; k < 2; ++k) dst[m][k] = *(const LAS bf16x8*)(lds + PG8_SA(b, h) + aoff + m * 2048 + k * 1024); } while (0)
; #define PG8_LDB(dst, b, h) do { _Pragma("unroll") for (int n = 0; n < 2; ++n) _Pragma("unroll") for (int k = 0; k < 2; ++k) dst[n][k] = *(const LAS bf16x8*)(lds + PG8_SB(b, h) + boff + n * 2048 + k * 1024); } while (0)
; #define PG8_MMA(ai, bj, At, Bt) do { __builtin_amdgcn_s_setprio(1); _Pragma("unroll") for (int m = 0; m < 4; ++m) _Pragma("unroll") for (int n = 0; n < 2; ++n) _Pragma("unroll") for (int k = 0; k < 2; ++k) \
;         acc[ai][bj][m][n] = __builtin_amdgcn_mfma_f32_16x16x32_bf16(Bt[n][k], At[m][k], acc[ai][bj][m][n], 0, 0, 0); __builtin_amdgcn_s_setprio(0); } while (0)
; #define PG8_WAIT_V(n) asm volatile("s_waitcnt vmcnt(" #n ")" ::: "memory")
; #define PG8_WAIT_L(n) asm volatile("s_waitcnt lgkmcnt(" #n ")" ::: "memory")
; #define PG8_BAR __builtin_amdgcn_s_barrier()
; #define PG8_SCHED __builtin_amdgcn_sched_barrier(0)
; template <class Epi, class Sched, bool ALIGN_EPI>
; __device__ __forceinline__ void gemm_phase(LAS unsigned char* lds, const int wid, const int lda_, const int ldb_, const int K_, const Sched& S, const Epi& E) {
;     ...
;         const bool has_next = S.next(ui + 1, nxt);
;         const int nt = S.nt(cur);
;         const char* nA = has_next ? S.a(nxt) : cA; const char* nB = has_next ? S.b(nxt) : cB;
; #pragma unroll 1
;         for (int t = 0; t < nt; t += 2) {
;             const bool last = (t == nt - 2);
;             const char* a1 = cA + (size_t)(t + 1) * kstep;
;             const char* a2 = last ? nA : cA + (size_t)(t + 2) * kstep; const char* b2 = last ? nB : cB + (size_t)(t + 2) * kstep;
;             const char* a3 = a2 + kstep; const char* b3 = b2 + kstep;
;             PG8_LDB(B0, 0, 0); PG8_LDB(B1, 0, 1); PG8_SCHED; PG8_LDA(At, 0, 0); PG8_STAGE(PG8_SA(1, 1), a1 + hstepA, voffA);
;             PG8_WAIT_V(8); PG8_WAIT_L(0); PG8_BAR; PG8_MMA(0, 0, At, B0); PG8_MMA(0, 1, At, B1); PG8_BAR; PG8_SCHED;
.LBB0_1119:
	v_mov_b64_e32 v[0:1], s[0:1]
	s_ashr_i32 s45, s44, 31
	v_cmp_lt_i64_e32 vcc, s[4:5], v[0:1]
	s_lshl_b64 s[4:5], s[44:45], 20
	v_readlane_b32 s46, v253, 52
	v_readlane_b32 s47, v253, 53
	s_add_u32 s46, s46, s4
	s_addc_u32 s47, s47, s5
	s_and_b64 s[4:5], vcc, exec
	s_cselect_b32 s4, s47, s41
	s_cselect_b32 s5, s46, s40
	s_ashr_i32 s43, s42, 31
	s_lshl_b64 s[48:49], s[42:43], 20
	s_add_u32 s48, s15, s48
	s_addc_u32 s49, s26, s49
	s_and_b64 s[76:77], vcc, exec
	s_cselect_b32 s43, s49, s51
	s_cselect_b32 s45, s48, s50
	s_add_u32 s76, s40, 0x80
	s_addc_u32 s77, s41, 0
	v_lshl_add_u64 v[156:157], s[76:77], 0, v[152:153]
	v_lshl_add_u64 v[158:159], s[76:77], 0, v[154:155]
	s_add_u32 s76, s50, 0x100
	s_addc_u32 s77, s51, 0
	s_mov_b32 s78, -2
	s_mov_b64 s[50:51], 0
	s_add_u32 s17, s40, s50
	s_addc_u32 s27, s41, s51
	s_add_u32 s17, s17, 0x100
	s_addc_u32 s27, s27, 0
	s_add_u32 s79, s76, s50
	s_addc_u32 s80, s77, s51
	s_add_i32 s86, 0, 0x10000
	s_cmpk_eq_i32 s50, 0xf00
	s_cselect_b32 s95, s4, s27
	s_cselect_b32 s94, s5, s17
	v_add_u32_e32 v141, s86, v135
	s_cselect_b32 s81, s43, s80
	s_cselect_b32 s80, s45, s79
	s_add_i32 s17, 0, 0x14000
	ds_read_b128 v[160:163], v141
	ds_read_b128 v[164:167], v141 offset:1024
	ds_read_b128 v[168:171], v141 offset:2048
	ds_read_b128 v[172:175], v141 offset:3072
	v_add_u32_e32 v141, s17, v135
	ds_read_b128 v[180:183], v141
	ds_read_b128 v[184:187], v141 offset:1024
	ds_read_b128 v[188:191], v141 offset:2048
	ds_read_b128 v[192:195], v141 offset:3072
	v_lshl_add_u64 v[228:229], v[158:159], 0, s[50:51]
	s_add_i32 m0, s16, 0xc000
	ds_read_b128 v[196:199], v139
	ds_read_b128 v[200:203], v139 offset:1024
	ds_read_b128 v[204:207], v139 offset:2048
	ds_read_b128 v[208:211], v139 offset:3072
	ds_read_b128 v[212:215], v139 offset:4096
	ds_read_b128 v[216:219], v139 offset:5120
	ds_read_b128 v[220:223], v139 offset:6144
	ds_read_b128 v[224:227], v139 offset:7168
	global_load_lds_dwordx4 v[228:229], off
	v_lshl_add_u64 v[228:229], v[156:157], 0, s[50:51]
	s_add_i32 m0, s16, 0xe000
	s_nop 0
	global_load_lds_dwordx4 v[228:229], off
	s_waitcnt vmcnt(8)
	s_waitcnt lgkmcnt(0)
	s_barrier
	v_readlane_b32 s101, v252, 58
	s_setprio 0
	s_cmp_eq_u32 s101, 0
	s_cbranch_scc1 .Lprio_dn_1120
	s_setprio 1
; #define PG8_STAGE(bufoff, gbase, voff) do { _Pragma("unroll") for (int _i = 0; _i < 2; ++_i) \
;         __builtin_amdgcn_global_load_lds((const unsigned*)((const char*)(gbase) + (voff)[_i]), (LAS unsigned*)(lds + (bufoff) + ldsw + _i * 8192), 16, 0, 0); } while (0)
; #define PG8_LDA(dst, b, h) do { _Pragma("unroll") for (int m = 0; m < 4; ++m) _Pragma("unroll") for (int k = 0; k < 2; ++k) dst[m][k] = *(const LAS bf16x8*)(lds + PG8_SA(b, h) + aoff + m * 2048 + k * 1024); } while (0)
; #define PG8_MMA(ai, bj, At, Bt) do { __builtin_amdgcn_s_setprio(1); _Pragma("unroll") for (int m = 0; m < 4; ++m) _Pragma("unroll") for (int n = 0; n < 2; ++n) _Pragma("unroll") for (int k = 0; k < 2; ++k) \
;         acc[ai][bj][m][n] = __builtin_amdgcn_mfma_f32_16x16x32_bf16(Bt[n][k], At[m][k], acc[ai][bj][m][n], 0, 0, 0); __builtin_amdgcn_s_setprio(0); } while (0)
; #define PG8_WAIT_V(n) asm volatile("s_waitcnt vmcnt(" #n ")" ::: "memory")
; #define PG8_WAIT_L(n) asm volatile("s_waitcnt lgkmcnt(" #n ")" ::: "memory")
; #define PG8_BAR __builtin_amdgcn_s_barrier()
; #define PG8_SCHED __builtin_amdgcn_sched_barrier(0)
; template <class Epi, class Sched, bool ALIGN_EPI>
; __device__ __forceinline__ void gemm_phase(LAS unsigned char* lds, const int wid, const int lda_, const int ldb_, const int K_, const Sched& S, const Epi& E) {
;     ...
;             PG8_WAIT_V(8); PG8_WAIT_L(0); PG8_BAR; PG8_MMA(0, 0, At, B0); PG8_MMA(0, 1, At, B1); PG8_BAR; PG8_SCHED;
;             PG8_LDA(At, 0, 1); PG8_STAGE(PG8_SB(0, 0), b2, voffB); PG8_STAGE(PG8_SB(0, 1), b2 + hstepB, voffB); PG8_STAGE(PG8_SA(0, 0), a2, voffA);
;             PG8_WAIT_V(8); PG8_WAIT_L(0); PG8_BAR; PG8_MMA(1, 0, At, B0); PG8_MMA(1, 1, At, B1); PG8_BAR; PG8_SCHED;
.Lprio_dn_1120:
	s_waitcnt lgkmcnt(0)
	v_mfma_f32_16x16x32_bf16 v[124:127], v[160:163], v[196:199], 0
	v_mfma_f32_16x16x32_bf16 v[120:123], v[168:171], v[196:199], 0
	v_mfma_f32_16x16x32_bf16 v[116:119], v[160:163], v[204:207], 0
	v_mfma_f32_16x16x32_bf16 v[112:115], v[168:171], v[204:207], 0
	v_mfma_f32_16x16x32_bf16 v[100:103], v[160:163], v[212:215], 0
	v_mfma_f32_16x16x32_bf16 v[96:99], v[168:171], v[212:215], 0
	v_mfma_f32_16x16x32_bf16 v[84:87], v[160:163], v[220:223], 0
	v_mfma_f32_16x16x32_bf16 v[80:83], v[168:171], v[220:223], 0
	v_mfma_f32_16x16x32_bf16 v[124:127], v[164:167], v[200:203], v[124:127]
	v_mfma_f32_16x16x32_bf16 v[120:123], v[172:175], v[200:203], v[120:123]
	v_mfma_f32_16x16x32_bf16 v[116:119], v[164:167], v[208:211], v[116:119]
	v_mfma_f32_16x16x32_bf16 v[112:115], v[172:175], v[208:211], v[112:115]
	v_mfma_f32_16x16x32_bf16 v[100:103], v[164:167], v[216:219], v[100:103]
	v_mfma_f32_16x16x32_bf16 v[96:99], v[172:175], v[216:219], v[96:99]
	v_mfma_f32_16x16x32_bf16 v[84:87], v[164:167], v[224:227], v[84:87]
	v_mfma_f32_16x16x32_bf16 v[80:83], v[172:175], v[224:227], v[80:83]
	v_mfma_f32_16x16x32_bf16 v[108:111], v[180:183], v[196:199], 0
	v_mfma_f32_16x16x32_bf16 v[104:107], v[188:191], v[196:199], 0
	v_mfma_f32_16x16x32_bf16 v[92:95], v[180:183], v[204:207], 0
	v_mfma_f32_16x16x32_bf16 v[88:91], v[188:191], v[204:207], 0
	v_mfma_f32_16x16x32_bf16 v[76:79], v[180:183], v[212:215], 0
	v_mfma_f32_16x16x32_bf16 v[72:75], v[188:191], v[212:215], 0
	v_mfma_f32_16x16x32_bf16 v[68:71], v[180:183], v[220:223], 0
	v_mfma_f32_16x16x32_bf16 v[64:67], v[188:191], v[220:223], 0
	v_mfma_f32_16x16x32_bf16 v[108:111], v[184:187], v[200:203], v[108:111]
	v_mfma_f32_16x16x32_bf16 v[104:107], v[192:195], v[200:203], v[104:107]
	v_mfma_f32_16x16x32_bf16 v[92:95], v[184:187], v[208:211], v[92:95]
	v_mfma_f32_16x16x32_bf16 v[88:91], v[192:195], v[208:211], v[88:91]
	v_mfma_f32_16x16x32_bf16 v[76:79], v[184:187], v[216:219], v[76:79]
	v_mfma_f32_16x16x32_bf16 v[72:75], v[192:195], v[216:219], v[72:75]
	v_mfma_f32_16x16x32_bf16 v[68:71], v[184:187], v[224:227], v[68:71]
	v_mfma_f32_16x16x32_bf16 v[64:67], v[192:195], v[224:227], v[64:67]
	s_barrier
	s_add_i32 s27, s86, s3
	v_lshl_add_u64 v[228:229], s[80:81], 0, v[176:177]
	s_mov_b32 m0, s27
	ds_read_b128 v[196:199], v139 offset:16384
	ds_read_b128 v[200:203], v139 offset:17408
	ds_read_b128 v[204:207], v139 offset:18432
	ds_read_b128 v[208:211], v139 offset:19456
	ds_read_b128 v[212:215], v139 offset:20480
	ds_read_b128 v[216:219], v139 offset:21504
	ds_read_b128 v[220:223], v139 offset:22528
	ds_read_b128 v[224:227], v139 offset:23552
	global_load_lds_dwordx4 v[228:229], off
	s_add_i32 m0, s27, 0x2000
	v_lshl_add_u64 v[230:231], s[80:81], 0, v[128:129]
	s_add_u32 s80, s80, s30
	s_addc_u32 s81, s81, s31
	s_add_i32 s17, s17, s3
	global_load_lds_dwordx4 v[230:231], off
	v_lshl_add_u64 v[232:233], s[80:81], 0, v[176:177]
	s_mov_b32 m0, s17
	v_lshl_add_u64 v[234:235], s[80:81], 0, v[128:129]
	global_load_lds_dwordx4 v[232:233], off
	s_add_i32 m0, s17, 0x2000
	v_lshl_add_u64 v[236:237], s[94:95], 0, v[132:133]
	global_load_lds_dwordx4 v[234:235], off
	s_mov_b32 m0, s16
	v_lshl_add_u64 v[246:247], s[94:95], 0, v[130:131]
	global_load_lds_dwordx4 v[236:237], off
	s_mov_b32 m0, s35
	s_nop 0
	global_load_lds_dwordx4 v[246:247], off
	s_waitcnt vmcnt(8)
	s_waitcnt lgkmcnt(0)
	s_barrier
	s_waitcnt lgkmcnt(0)
	v_mfma_f32_16x16x32_bf16 v[60:63], v[160:163], v[196:199], 0
	v_mfma_f32_16x16x32_bf16 v[56:59], v[168:171], v[196:199], 0
	v_mfma_f32_16x16x32_bf16 v[52:55], v[160:163], v[204:207], 0
	v_mfma_f32_16x16x32_bf16 v[48:51], v[168:171], v[204:207], 0
	v_mfma_f32_16x16x32_bf16 v[36:39], v[160:163], v[212:215], 0
	v_mfma_f32_16x16x32_bf16 v[32:35], v[168:171], v[212:215], 0
	v_mfma_f32_16x16x32_bf16 v[20:23], v[160:163], v[220:223], 0
	v_mfma_f32_16x16x32_bf16 v[16:19], v[168:171], v[220:223], 0
	v_mfma_f32_16x16x32_bf16 v[60:63], v[164:167], v[200:203], v[60:63]
	v_mfma_f32_16x16x32_bf16 v[56:59], v[172:175], v[200:203], v[56:59]
	v_mfma_f32_16x16x32_bf16 v[52:55], v[164:167], v[208:211], v[52:55]
	v_mfma_f32_16x16x32_bf16 v[48:51], v[172:175], v[208:211], v[48:51]
	v_mfma_f32_16x16x32_bf16 v[36:39], v[164:167], v[216:219], v[36:39]
	v_mfma_f32_16x16x32_bf16 v[32:35], v[172:175], v[216:219], v[32:35]
	v_mfma_f32_16x16x32_bf16 v[20:23], v[164:167], v[224:227], v[20:23]
	v_mfma_f32_16x16x32_bf16 v[16:19], v[172:175], v[224:227], v[16:19]
	v_mfma_f32_16x16x32_bf16 v[44:47], v[180:183], v[196:199], 0
	v_mfma_f32_16x16x32_bf16 v[40:43], v[188:191], v[196:199], 0
	v_mfma_f32_16x16x32_bf16 v[28:31], v[180:183], v[204:207], 0
	v_mfma_f32_16x16x32_bf16 v[24:27], v[188:191], v[204:207], 0
	v_mfma_f32_16x16x32_bf16 v[12:15], v[180:183], v[212:215], 0
	v_mfma_f32_16x16x32_bf16 v[8:11], v[188:191], v[212:215], 0
	v_mfma_f32_16x16x32_bf16 v[4:7], v[180:183], v[220:223], 0
	v_mfma_f32_16x16x32_bf16 v[0:3], v[188:191], v[220:223], 0
	v_mfma_f32_16x16x32_bf16 v[44:47], v[184:187], v[200:203], v[44:47]
	v_mfma_f32_16x16x32_bf16 v[40:43], v[192:195], v[200:203], v[40:43]
	v_mfma_f32_16x16x32_bf16 v[28:31], v[184:187], v[208:211], v[28:31]
	v_mfma_f32_16x16x32_bf16 v[24:27], v[192:195], v[208:211], v[24:27]
	v_mfma_f32_16x16x32_bf16 v[12:15], v[184:187], v[216:219], v[12:15]
	v_mfma_f32_16x16x32_bf16 v[8:11], v[192:195], v[216:219], v[8:11]
	v_mfma_f32_16x16x32_bf16 v[4:7], v[184:187], v[224:227], v[4:7]
	v_mfma_f32_16x16x32_bf16 v[0:3], v[192:195], v[224:227], v[0:3]
	s_barrier
	s_branch .Lgemm_join_1120

; #define PG8_STAGE(bufoff, gbase, voff) do { _Pragma("unroll") for (int _i = 0; _i < 2; ++_i) \
;         __builtin_amdgcn_global_load_lds((const unsigned*)((const char*)(gbase) + (voff)[_i]), (LAS unsigned*)(lds + (bufoff) + ldsw + _i * 8192), 16, 0, 0); } while (0)
; #define PG8_LDA(dst, b, h) do { _Pragma("unroll") for (int m = 0; m < 4; ++m) _Pragma("unroll") for (int k = 0; k < 2; ++k) dst[m][k] = *(const LAS bf16x8*)(lds + PG8_SA(b, h) + aoff + m * 2048 + k * 1024); } while (0)
; #define PG8_LDB(dst, b, h) do { _Pragma("unroll") for (int n = 0; n < 2; ++n) _Pragma("unroll") for (int k = 0; k < 2; ++k) dst[n][k] = *(const LAS bf16x8*)(lds + PG8_SB(b, h) + boff + n * 2048 + k * 1024); } while (0)
; #define PG8_MMA(ai, bj, At, Bt) do { __builtin_amdgcn_s_setprio(1); _Pragma("unroll") for (int m = 0; m < 4; ++m) _Pragma("unroll") for (int n = 0; n < 2; ++n) _Pragma("unroll") for (int k = 0; k < 2; ++k) \
;         acc[ai][bj][m][n] = __builtin_amdgcn_mfma_f32_16x16x32_bf16(Bt[n][k], At[m][k], acc[ai][bj][m][n], 0, 0, 0); __builtin_amdgcn_s_setprio(0); } while (0)
; #define PG8_WAIT_V(n) asm volatile("s_waitcnt vmcnt(" #n ")" ::: "memory")
; #define PG8_WAIT_L(n) asm volatile("s_waitcnt lgkmcnt(" #n ")" ::: "memory")
; #define PG8_BAR __builtin_amdgcn_s_barrier()
; #define PG8_SCHED __builtin_amdgcn_sched_barrier(0)
; template <class Epi, class Sched, bool ALIGN_EPI>
; __device__ __forceinline__ void gemm_phase(LAS unsigned char* lds, const int wid, const int lda_, const int ldb_, const int K_, const Sched& S, const Epi& E) {
;     ...
;         const bool has_next = S.next(ui + 1, nxt);
;         const int nt = S.nt(cur);
;         const char* nA = has_next ? S.a(nxt) : cA; const char* nB = has_next ? S.b(nxt) : cB;
; #pragma unroll 1
;         for (int t = 0; t < nt; t += 2) {
;             const bool last = (t == nt - 2);
;             const char* a1 = cA + (size_t)(t + 1) * kstep;
;             const char* a2 = last ? nA : cA + (size_t)(t + 2) * kstep; const char* b2 = last ? nB : cB + (size_t)(t + 2) * kstep;
;             const char* a3 = a2 + kstep; const char* b3 = b2 + kstep;
;             PG8_LDB(B0, 0, 0); PG8_LDB(B1, 0, 1); PG8_SCHED; PG8_LDA(At, 0, 0); PG8_STAGE(PG8_SA(1, 1), a1 + hstepA, voffA);
;             PG8_WAIT_V(8); PG8_WAIT_L(0); PG8_BAR; PG8_MMA(0, 0, At, B0); PG8_MMA(0, 1, At, B1); PG8_BAR; PG8_SCHED;
.LBB0_1340:
	s_cmp_gt_i32 s38, -1
	s_cselect_b64 s[44:45], -1, 0
	s_cmp_lt_i32 s38, 0
	s_cselect_b32 s4, 0x58, 22
	s_add_i32 s5, s4, -2
	s_add_u32 s46, s46, 0x80
	s_addc_u32 s47, s47, 0
	s_add_u32 s31, s48, 0x100
	s_mov_b32 s39, 0
	s_addc_u32 s35, s49, 0
	s_add_i32 s76, s39, 2
	s_add_u32 s17, s46, 0x80
	s_addc_u32 s27, s47, 0
	s_add_i32 s77, 0, 0x10000
	s_cmp_eq_u32 s5, s39
	s_cselect_b32 s49, s43, s27
	s_cselect_b32 s48, s42, s17
	v_add_u32_e32 v141, s77, v135
	s_cselect_b32 s79, s37, s35
	s_cselect_b32 s78, s36, s31
	s_add_i32 s17, 0, 0x14000
	ds_read_b128 v[156:159], v141
	ds_read_b128 v[160:163], v141 offset:1024
	ds_read_b128 v[164:167], v141 offset:2048
	ds_read_b128 v[168:171], v141 offset:3072
	v_add_u32_e32 v141, s17, v135
	ds_read_b128 v[172:175], v141
	ds_read_b128 v[180:183], v141 offset:1024
	ds_read_b128 v[184:187], v141 offset:2048
	ds_read_b128 v[188:191], v141 offset:3072
	v_lshl_add_u64 v[224:225], s[46:47], 0, v[152:153]
	s_add_i32 m0, s16, 0xc000
	ds_read_b128 v[192:195], v139
	ds_read_b128 v[196:199], v139 offset:1024
	ds_read_b128 v[200:203], v139 offset:2048
	ds_read_b128 v[204:207], v139 offset:3072
	ds_read_b128 v[208:211], v139 offset:4096
	ds_read_b128 v[212:215], v139 offset:5120
	ds_read_b128 v[216:219], v139 offset:6144
	ds_read_b128 v[220:223], v139 offset:7168
	global_load_lds_dwordx4 v[224:225], off
	v_lshl_add_u64 v[224:225], s[46:47], 0, v[154:155]
	s_add_i32 m0, s16, 0xe000
	s_nop 0
	global_load_lds_dwordx4 v[224:225], off
	s_waitcnt vmcnt(8)
	s_waitcnt lgkmcnt(0)
	s_barrier
	v_readlane_b32 s101, v252, 58
	s_setprio 0
	s_cmp_eq_u32 s101, 0
	s_cbranch_scc1 .Lprio_dn_1341
	s_setprio 1
; #define PG8_STAGE(bufoff, gbase, voff) do { _Pragma("unroll") for (int _i = 0; _i < 2; ++_i) \
;         __builtin_amdgcn_global_load_lds((const unsigned*)((const char*)(gbase) + (voff)[_i]), (LAS unsigned*)(lds + (bufoff) + ldsw + _i * 8192), 16, 0, 0); } while (0)
; #define PG8_LDA(dst, b, h) do { _Pragma("unroll") for (int m = 0; m < 4; ++m) _Pragma("unroll") for (int k = 0; k < 2; ++k) dst[m][k] = *(const LAS bf16x8*)(lds + PG8_SA(b, h) + aoff + m * 2048 + k * 1024); } while (0)
; #define PG8_MMA(ai, bj, At, Bt) do { __builtin_amdgcn_s_setprio(1); _Pragma("unroll") for (int m = 0; m < 4; ++m) _Pragma("unroll") for (int n = 0; n < 2; ++n) _Pragma("unroll") for (int k = 0; k < 2; ++k) \
;         acc[ai][bj][m][n] = __builtin_amdgcn_mfma_f32_16x16x32_bf16(Bt[n][k], At[m][k], acc[ai][bj][m][n], 0, 0, 0); __builtin_amdgcn_s_setprio(0); } while (0)
; #define PG8_WAIT_V(n) asm volatile("s_waitcnt vmcnt(" #n ")" ::: "memory")
; #define PG8_WAIT_L(n) asm volatile("s_waitcnt lgkmcnt(" #n ")" ::: "memory")
; #define PG8_BAR __builtin_amdgcn_s_barrier()
; #define PG8_SCHED __builtin_amdgcn_sched_barrier(0)
; template <class Epi, class Sched, bool ALIGN_EPI>
; __device__ __forceinline__ void gemm_phase(LAS unsigned char* lds, const int wid, const int lda_, const int ldb_, const int K_, const Sched& S, const Epi& E) {
;     ...
;             PG8_WAIT_V(8); PG8_WAIT_L(0); PG8_BAR; PG8_MMA(0, 0, At, B0); PG8_MMA(0, 1, At, B1); PG8_BAR; PG8_SCHED;
;             PG8_LDA(At, 0, 1); PG8_STAGE(PG8_SB(0, 0), b2, voffB); PG8_STAGE(PG8_SB(0, 1), b2 + hstepB, voffB); PG8_STAGE(PG8_SA(0, 0), a2, voffA);
;             PG8_WAIT_V(8); PG8_WAIT_L(0); PG8_BAR; PG8_MMA(1, 0, At, B0); PG8_MMA(1, 1, At, B1); PG8_BAR; PG8_SCHED;
.Lprio_dn_1341:
	s_waitcnt lgkmcnt(0)
	v_mfma_f32_16x16x32_bf16 v[124:127], v[156:159], v[192:195], 0
	v_mfma_f32_16x16x32_bf16 v[120:123], v[164:167], v[192:195], 0
	v_mfma_f32_16x16x32_bf16 v[116:119], v[156:159], v[200:203], 0
	v_mfma_f32_16x16x32_bf16 v[112:115], v[164:167], v[200:203], 0
	v_mfma_f32_16x16x32_bf16 v[100:103], v[156:159], v[208:211], 0
	v_mfma_f32_16x16x32_bf16 v[96:99], v[164:167], v[208:211], 0
	v_mfma_f32_16x16x32_bf16 v[84:87], v[156:159], v[216:219], 0
	v_mfma_f32_16x16x32_bf16 v[80:83], v[164:167], v[216:219], 0
	v_mfma_f32_16x16x32_bf16 v[124:127], v[160:163], v[196:199], v[124:127]
	v_mfma_f32_16x16x32_bf16 v[120:123], v[168:171], v[196:199], v[120:123]
	v_mfma_f32_16x16x32_bf16 v[116:119], v[160:163], v[204:207], v[116:119]
	v_mfma_f32_16x16x32_bf16 v[112:115], v[168:171], v[204:207], v[112:115]
	v_mfma_f32_16x16x32_bf16 v[100:103], v[160:163], v[212:215], v[100:103]
	v_mfma_f32_16x16x32_bf16 v[96:99], v[168:171], v[212:215], v[96:99]
	v_mfma_f32_16x16x32_bf16 v[84:87], v[160:163], v[220:223], v[84:87]
	v_mfma_f32_16x16x32_bf16 v[80:83], v[168:171], v[220:223], v[80:83]
	v_mfma_f32_16x16x32_bf16 v[108:111], v[172:175], v[192:195], 0
	v_mfma_f32_16x16x32_bf16 v[104:107], v[184:187], v[192:195], 0
	v_mfma_f32_16x16x32_bf16 v[92:95], v[172:175], v[200:203], 0
	v_mfma_f32_16x16x32_bf16 v[88:91], v[184:187], v[200:203], 0
	v_mfma_f32_16x16x32_bf16 v[76:79], v[172:175], v[208:211], 0
	v_mfma_f32_16x16x32_bf16 v[72:75], v[184:187], v[208:211], 0
	v_mfma_f32_16x16x32_bf16 v[68:71], v[172:175], v[216:219], 0
	v_mfma_f32_16x16x32_bf16 v[64:67], v[184:187], v[216:219], 0
	v_mfma_f32_16x16x32_bf16 v[108:111], v[180:183], v[196:199], v[108:111]
	v_mfma_f32_16x16x32_bf16 v[104:107], v[188:191], v[196:199], v[104:107]
	v_mfma_f32_16x16x32_bf16 v[92:95], v[180:183], v[204:207], v[92:95]
	v_mfma_f32_16x16x32_bf16 v[88:91], v[188:191], v[204:207], v[88:91]
	v_mfma_f32_16x16x32_bf16 v[76:79], v[180:183], v[212:215], v[76:79]
	v_mfma_f32_16x16x32_bf16 v[72:75], v[188:191], v[212:215], v[72:75]
	v_mfma_f32_16x16x32_bf16 v[68:71], v[180:183], v[220:223], v[68:71]
	v_mfma_f32_16x16x32_bf16 v[64:67], v[188:191], v[220:223], v[64:67]
	s_barrier
	s_add_i32 s27, s77, s3
	v_lshl_add_u64 v[224:225], s[78:79], 0, v[176:177]
	s_mov_b32 m0, s27
	ds_read_b128 v[192:195], v139 offset:16384
	ds_read_b128 v[196:199], v139 offset:17408
	ds_read_b128 v[200:203], v139 offset:18432
	ds_read_b128 v[204:207], v139 offset:19456
	ds_read_b128 v[208:211], v139 offset:20480
	ds_read_b128 v[212:215], v139 offset:21504
	ds_read_b128 v[216:219], v139 offset:22528
	ds_read_b128 v[220:223], v139 offset:23552
	global_load_lds_dwordx4 v[224:225], off
	s_add_i32 m0, s27, 0x2000
	v_lshl_add_u64 v[226:227], s[78:79], 0, v[132:133]
	s_add_u32 s78, s78, s10
	s_addc_u32 s79, s79, s11
	s_add_i32 s17, s17, s3
	global_load_lds_dwordx4 v[226:227], off
	v_lshl_add_u64 v[228:229], s[78:79], 0, v[176:177]
	s_mov_b32 m0, s17
	v_lshl_add_u64 v[230:231], s[78:79], 0, v[132:133]
	global_load_lds_dwordx4 v[228:229], off
	s_add_i32 m0, s17, 0x2000
	v_lshl_add_u64 v[232:233], s[48:49], 0, v[128:129]
	global_load_lds_dwordx4 v[230:231], off
	s_mov_b32 m0, s16
	v_lshl_add_u64 v[234:235], s[48:49], 0, v[130:131]
	global_load_lds_dwordx4 v[232:233], off
	s_mov_b32 m0, s14
	s_nop 0
	global_load_lds_dwordx4 v[234:235], off
	s_waitcnt vmcnt(8)
	s_waitcnt lgkmcnt(0)
	s_barrier
	s_waitcnt lgkmcnt(0)
	v_mfma_f32_16x16x32_bf16 v[60:63], v[156:159], v[192:195], 0
	v_mfma_f32_16x16x32_bf16 v[56:59], v[164:167], v[192:195], 0
	v_mfma_f32_16x16x32_bf16 v[52:55], v[156:159], v[200:203], 0
	v_mfma_f32_16x16x32_bf16 v[48:51], v[164:167], v[200:203], 0
	v_mfma_f32_16x16x32_bf16 v[36:39], v[156:159], v[208:211], 0
	v_mfma_f32_16x16x32_bf16 v[32:35], v[164:167], v[208:211], 0
	v_mfma_f32_16x16x32_bf16 v[20:23], v[156:159], v[216:219], 0
	v_mfma_f32_16x16x32_bf16 v[16:19], v[164:167], v[216:219], 0
	v_mfma_f32_16x16x32_bf16 v[60:63], v[160:163], v[196:199], v[60:63]
	v_mfma_f32_16x16x32_bf16 v[56:59], v[168:171], v[196:199], v[56:59]
	v_mfma_f32_16x16x32_bf16 v[52:55], v[160:163], v[204:207], v[52:55]
	v_mfma_f32_16x16x32_bf16 v[48:51], v[168:171], v[204:207], v[48:51]
	v_mfma_f32_16x16x32_bf16 v[36:39], v[160:163], v[212:215], v[36:39]
	v_mfma_f32_16x16x32_bf16 v[32:35], v[168:171], v[212:215], v[32:35]
	v_mfma_f32_16x16x32_bf16 v[20:23], v[160:163], v[220:223], v[20:23]
	v_mfma_f32_16x16x32_bf16 v[16:19], v[168:171], v[220:223], v[16:19]
	v_mfma_f32_16x16x32_bf16 v[44:47], v[172:175], v[192:195], 0
	v_mfma_f32_16x16x32_bf16 v[40:43], v[184:187], v[192:195], 0
	v_mfma_f32_16x16x32_bf16 v[28:31], v[172:175], v[200:203], 0
	v_mfma_f32_16x16x32_bf16 v[24:27], v[184:187], v[200:203], 0
	v_mfma_f32_16x16x32_bf16 v[12:15], v[172:175], v[208:211], 0
	v_mfma_f32_16x16x32_bf16 v[8:11], v[184:187], v[208:211], 0
	v_mfma_f32_16x16x32_bf16 v[4:7], v[172:175], v[216:219], 0
	v_mfma_f32_16x16x32_bf16 v[0:3], v[184:187], v[216:219], 0
	v_mfma_f32_16x16x32_bf16 v[44:47], v[180:183], v[196:199], v[44:47]
	v_mfma_f32_16x16x32_bf16 v[40:43], v[188:191], v[196:199], v[40:43]
	v_mfma_f32_16x16x32_bf16 v[28:31], v[180:183], v[204:207], v[28:31]
	v_mfma_f32_16x16x32_bf16 v[24:27], v[188:191], v[204:207], v[24:27]
	v_mfma_f32_16x16x32_bf16 v[12:15], v[180:183], v[212:215], v[12:15]
	v_mfma_f32_16x16x32_bf16 v[8:11], v[188:191], v[212:215], v[8:11]
	v_mfma_f32_16x16x32_bf16 v[4:7], v[180:183], v[220:223], v[4:7]
	v_mfma_f32_16x16x32_bf16 v[0:3], v[188:191], v[220:223], v[0:3]
	s_barrier
	s_branch .Lgemm_join_1341
